# speedup vs baseline: 1.0210x; 1.0210x over previous
; __global__ void __launch_bounds__(512, 2) mega_fwd(Args a_in) {
;     ...
;         { float d1 = 0.f, d2 = 0.f;
; #pragma unroll
;           for (int i = 0; i < 2; ++i) { d1 += a.lq1[lane + 64 * i] * a.lk1[lane + 64 * i]; d2 += a.lq2[lane + 64 * i] * a.lk2[lane + 64 * i]; }
;           d1 = wave_sum(d1); d2 = wave_sum(d2); lam = __expf(d1) - __expf(d2) + LAMBDA_INIT; }
;         unsigned* qsl = (unsigned*)(lds + att::SHM_ATTN);
;         if (tid == 0) ((float*)qsl)[1] = lam;
.LBB0_664:
	s_or_b64 exec, exec, s[6:7]
	v_readlane_b32 s8, v244, 5
	v_readlane_b32 s9, v244, 6
	s_waitcnt lgkmcnt(0)
	s_barrier
	v_and_b32_e32 v249, 63, v175
	v_lshrrev_b32_e32 v250, 6, v175
	v_lshlrev_b32_e32 v248, 11, v250
	v_lshrrev_b32_e32 v245, 4, v249
	v_and_b32_e32 v246, 15, v249
	v_xor_b32_e32 v246, v246, v245
	v_lshlrev_b32_e32 v246, 4, v246
	v_lshl_add_u32 v245, v245, 12, v246
	v_lshl_add_u32 v245, v250, 15, v245
	v_and_b32_e32 v246, 64, v246
	v_lshlrev_b32_e32 v246, 1, v246
	v_sub_u32_e32 v246, v245, v246
	v_add_u32_e32 v246, 0x4040, v246
	v_bfe_u32 v247, v249, 2, 2
	v_and_b32_e32 v251, 1, v250
	v_lshl_or_b32 v247, v251, 2, v247
	v_bfe_u32 v251, v249, 4, 1
	v_lshl_or_b32 v247, v251, 3, v247
	v_lshrrev_b32_e32 v251, 1, v250
	v_lshl_or_b32 v247, v251, 4, v247
	v_lshlrev_b32_e32 v247, 12, v247
	v_lshrrev_b32_e32 v251, 5, v249
	v_lshl_or_b32 v247, v251, 6, v247
	v_and_b32_e32 v251, 3, v249
	v_lshl_or_b32 v247, v251, 4, v247
	s_load_dwordx8 s[0:7], s[8:9], 0x38
	s_load_dwordx2 s[10:11], s[8:9], 0x98
	v_mov_b32_e32 v4, v175
	v_cmp_lt_i32_e32 vcc, v18, v16
	v_and_b32_e32 v0, 63, v4
	v_lshlrev_b32_e32 v0, 2, v0
	s_waitcnt lgkmcnt(0)
	global_load_dword v1, v0, s[0:1]
	global_load_dword v2, v0, s[2:3]
	global_load_dword v3, v0, s[4:5]
	global_load_dword v5, v0, s[6:7]
	global_load_dword v6, v0, s[0:1] offset:256
	global_load_dword v7, v0, s[2:3] offset:256
	global_load_dword v8, v0, s[4:5] offset:256
	global_load_dword v9, v0, s[6:7] offset:256
	v_cndmask_b32_e32 v0, v13, v18, vcc
	v_lshlrev_b32_e32 v206, 2, v0
	v_cmp_lt_i32_e32 vcc, v17, v16
	v_xor_b32_e32 v11, 4, v13
	v_xor_b32_e32 v12, 8, v13
	v_cndmask_b32_e32 v10, v13, v17, vcc
	v_lshlrev_b32_e32 v207, 2, v10
	v_cmp_lt_i32_e32 vcc, v11, v16
	v_writelane_b32 v244, s10, 27
	v_mov_b32_e32 v171, 0
	s_mov_b32 s17, 0
	v_writelane_b32 v244, s11, 28
	v_cmp_eq_u32_e64 s[0:1], 0, v4
	s_waitcnt vmcnt(6)
	v_fma_f32 v0, v1, v2, 0
	s_waitcnt vmcnt(4)
	v_fma_f32 v1, v3, v5, 0
	v_xor_b32_e32 v5, 16, v13
	s_waitcnt vmcnt(2)
	v_fmac_f32_e32 v0, v6, v7
	ds_bpermute_b32 v2, v206, v0
	s_waitcnt vmcnt(0)
	v_fmac_f32_e32 v1, v8, v9
	ds_bpermute_b32 v3, v206, v1
	v_cndmask_b32_e32 v7, v13, v11, vcc
	v_lshlrev_b32_e32 v208, 2, v7
	s_waitcnt lgkmcnt(1)
	v_add_f32_e32 v0, v0, v2
	ds_bpermute_b32 v2, v207, v0
	s_waitcnt lgkmcnt(1)
	v_add_f32_e32 v1, v1, v3
	ds_bpermute_b32 v3, v207, v1
	v_cmp_lt_i32_e32 vcc, v12, v16
	v_xor_b32_e32 v6, 32, v13
	s_waitcnt lgkmcnt(1)
	v_add_f32_e32 v0, v0, v2
	ds_bpermute_b32 v2, v208, v0
	s_waitcnt lgkmcnt(1)
	v_add_f32_e32 v1, v1, v3
	ds_bpermute_b32 v3, v208, v1
	v_cndmask_b32_e32 v7, v13, v12, vcc
	v_lshlrev_b32_e32 v209, 2, v7
	s_waitcnt lgkmcnt(1)
	v_add_f32_e32 v0, v0, v2
	ds_bpermute_b32 v2, v209, v0
	s_waitcnt lgkmcnt(1)
	v_add_f32_e32 v1, v1, v3
	ds_bpermute_b32 v3, v209, v1
	v_cmp_lt_i32_e32 vcc, v5, v16
	s_waitcnt lgkmcnt(1)
	v_add_f32_e32 v0, v0, v2
	v_cndmask_b32_e32 v5, v13, v5, vcc
	v_lshlrev_b32_e32 v177, 2, v5
	s_waitcnt lgkmcnt(0)
	v_add_f32_e32 v2, v1, v3
	ds_bpermute_b32 v1, v177, v0
	ds_bpermute_b32 v3, v177, v2
	v_cmp_lt_i32_e32 vcc, v6, v16
	s_waitcnt lgkmcnt(1)
	v_add_f32_e32 v1, v0, v1
	v_cndmask_b32_e32 v5, v13, v6, vcc
	v_lshlrev_b32_e32 v204, 2, v5
	s_waitcnt lgkmcnt(0)
	v_add_f32_e32 v0, v2, v3
	ds_bpermute_b32 v3, v204, v1
	ds_bpermute_b32 v2, v204, v0
	s_mov_b64 s[4:5], exec
	v_writelane_b32 v244, s0, 29
	s_nop 1
	v_writelane_b32 v244, s1, 30
	s_and_b64 s[0:1], s[4:5], s[0:1]
	s_mov_b64 exec, s[0:1]
	s_cbranch_execz .LBB0_666
	s_waitcnt lgkmcnt(1)
	v_add_f32_e32 v1, v1, v3
	s_waitcnt lgkmcnt(0)
	v_add_f32_e32 v0, v0, v2
	v_mul_f32_e32 v1, 0x3fb8aa3b, v1
	v_mul_f32_e32 v0, 0x3fb8aa3b, v0
	v_exp_f32_e32 v1, v1
	v_exp_f32_e32 v0, v0
	s_add_i32 s0, 0, 0x10804
	v_sub_f32_e32 v0, v1, v0
	v_add_f32_e32 v0, 0x3eb60549, v0
	v_mov_b32_e32 v1, s0
	ds_write_b32 v1, v0

; __device__ __forceinline__ void finishSM(f32x16& p0, f32x16& p1, float& l_reg, bf16x8& pa0, bf16x8& pa1, bf16x8& pa2, bf16x8& pa3) {
; #pragma unroll
;   for (int r = 0; r < 16; ++r) p0[r] = __builtin_amdgcn_exp2f(p0[r]);
; #pragma unroll
;   for (int r = 0; r < 16; ++r) p1[r] = __builtin_amdgcn_exp2f(p1[r]);
;   float ps = 0;
; #pragma unroll
;   for (int r = 0; r < 16; ++r) ps += p0[r];
; #pragma unroll
;   for (int r = 0; r < 16; ++r) ps += p1[r];
;   { auto rr = __builtin_amdgcn_permlane32_swap(__float_as_uint(ps), __float_as_uint(ps), false, false);
;     ps = __uint_as_float(rr[0]) + __uint_as_float(rr[1]); }
;   l_reg += ps;
;     ...
;   PK4(p0, 0, pa0); PK4(p0, 8, pa1); PK4(p1, 0, pa2); PK4(p1, 8, pa3);
;     ...
; }
; template <int MODE>
; __device__ __forceinline__ void qkt(f32x16& p0, f32x16& p1, const bf16* Ks, const bf16x8* qr, int r32, int hi, float dq, float nsl, int side, float mi) {
;   if (MODE == 0) {
;     if (side != 0) {
;       const float sg = side > 0 ? -nsl : nsl, bb = -sg * dq - mi;
; #pragma unroll
;       for (int r = 0; r < 16; ++r) { const float c = (float)((r & 3) + 8 * (r >> 2)); p0[r] = fmaf(c, sg, bb); p1[r] = fmaf(c + 32.f, sg, bb); }
;     } else {
; #pragma unroll
;       for (int r = 0; r < 16; ++r) { const float c = (float)((r & 3) + 8 * (r >> 2)); p0[r] = fmaf(fabsf(dq - c), nsl, -mi); p1[r] = fmaf(fabsf(dq - (c + 32.f)), nsl, -mi); }
;     }
;   } else {
; #pragma unroll
;     for (int r = 0; r < 16; ++r) { const float c = (float)((r & 3) + 8 * (r >> 2)); p0[r] = (r < 8) ? fmaf(fabsf(dq - c), nsl, -mi) : NEGBIG; p1[r] = NEGBIG; }
;   }
; #pragma unroll
;   for (int d0 = 0; d0 < 8; ++d0) {
;     const int ko = r32 * 256 + ((((d0 & 3) * 32 + hi * 16) ^ ((r32 & 7) << 4))) + (d0 >> 2) * 128;
;     bf16x8 b0 = *reinterpret_cast<const bf16x8*>((const char*)Ks + ko);
;     bf16x8 b1 = *reinterpret_cast<const bf16x8*>((const char*)Ks + ko + 8192);
;     p0 = __builtin_amdgcn_mfma_f32_32x32x16_bf16(b0, qr[d0], p0, 0, 0, 0);
;     p1 = __builtin_amdgcn_mfma_f32_32x32x16_bf16(b1, qr[d0], p1, 0, 0, 0); }
; template <int J> ...
;     ...
;     SBAR(); qkt<0>(pB0, pB1, (bf16*)((char*)K_lds + SHM_K), qr, r32, hi, TILE_DQ(j), nsl, TILE_SIDE(j), mi);
;     finishSM(pA0, pA1, l_reg, pa0, pa1, pa2, pa3); SBAR();
;     SLOAD(SO, j + SDEPTH); SBAR();
;     pv_d0(o, vb0, pa0, pa1, pa2, pa3); SBAR();
;     __syncthreads(); SWAIT(); SWRITE(0, SE);
.LBB0_697:
	v_readfirstlane_b32 s92, v248
	s_add_i32 s4, s6, s3
	s_add_i32 s10, s4, 1
	s_ashr_i32 s11, s10, 31
	s_lshl_b64 s[10:11], s[10:11], 18
	s_add_u32 s10, s89, s10
	s_addc_u32 s11, s24, s11
	s_add_i32 s5, s3, 1
	s_cmp_lt_i32 s5, s30
	s_cselect_b32 s10, s10, s16
	s_cselect_b32 s11, s11, s1
	s_ashr_i32 s5, s4, 31
	s_lshl_b64 s[4:5], s[4:5], 18
	s_add_u32 s4, s0, s4
	s_addc_u32 s5, s25, s5
	s_add_i32 m0, s92, 0x8000
	s_nop 0
	global_load_lds_dwordx4 v245, s[10:11]
	s_add_i32 m0, s92, 0x8400
	s_nop 0
	global_load_lds_dwordx4 v246, s[10:11]
	s_add_i32 m0, s92, 0x4000
	s_nop 0
	global_load_lds_dwordx4 v247, s[4:5]
	s_add_i32 m0, s92, 0x4380
	s_nop 0
	global_load_lds_dwordx4 v247, s[4:5] offset:128
	ds_read_b128 v[0:3], v230 offset:49152
	ds_read_b128 v[4:7], v230 offset:57344
	v_exp_f32_e32 v74, v74
	v_exp_f32_e32 v75, v75
	v_exp_f32_e32 v76, v76
	s_waitcnt lgkmcnt(1)
	v_mfma_f32_32x32x16_bf16 v[122:137], v[0:3], v[166:169], v[122:137]
	v_exp_f32_e32 v77, v77
	v_exp_f32_e32 v78, v78
	v_exp_f32_e32 v79, v79
	v_exp_f32_e32 v80, v80
	v_exp_f32_e32 v81, v81
	v_exp_f32_e32 v82, v82
	v_exp_f32_e32 v83, v83
	s_waitcnt lgkmcnt(0)
	v_mfma_f32_32x32x16_bf16 v[106:121], v[4:7], v[166:169], v[106:121]
	ds_read_b128 v[0:3], v231 offset:49152
	ds_read_b128 v[4:7], v231 offset:57344
	v_exp_f32_e32 v84, v84
	v_exp_f32_e32 v85, v85
	v_exp_f32_e32 v86, v86
	v_exp_f32_e32 v87, v87
	v_exp_f32_e32 v88, v88
	v_exp_f32_e32 v89, v89
	s_waitcnt lgkmcnt(1)
	v_mfma_f32_32x32x16_bf16 v[122:137], v[0:3], v[162:165], v[122:137]
	s_add_i32 s4, s3, 1
	s_waitcnt lgkmcnt(0)
	v_mfma_f32_32x32x16_bf16 v[106:121], v[4:7], v[162:165], v[106:121]
	ds_read_b128 v[0:3], v232 offset:49152
	ds_read_b128 v[4:7], v232 offset:57344
	s_waitcnt lgkmcnt(1)
	v_mfma_f32_32x32x16_bf16 v[122:137], v[0:3], v[158:161], v[122:137]
	s_waitcnt lgkmcnt(0)
	v_mfma_f32_32x32x16_bf16 v[106:121], v[4:7], v[158:161], v[106:121]
	ds_read_b128 v[0:3], v233 offset:49152
	ds_read_b128 v[4:7], v233 offset:57344
	s_waitcnt lgkmcnt(1)
	v_mfma_f32_32x32x16_bf16 v[122:137], v[0:3], v[154:157], v[122:137]
	s_waitcnt lgkmcnt(0)
	v_mfma_f32_32x32x16_bf16 v[106:121], v[4:7], v[154:157], v[106:121]
	ds_read_b128 v[0:3], v230 offset:49280
	ds_read_b128 v[4:7], v230 offset:57472
	s_waitcnt lgkmcnt(1)
	v_mfma_f32_32x32x16_bf16 v[122:137], v[0:3], v[150:153], v[122:137]
	s_waitcnt lgkmcnt(0)
	v_mfma_f32_32x32x16_bf16 v[106:121], v[4:7], v[150:153], v[106:121]
	ds_read_b128 v[0:3], v231 offset:49280
	ds_read_b128 v[4:7], v231 offset:57472
	s_waitcnt lgkmcnt(1)
	v_mfma_f32_32x32x16_bf16 v[122:137], v[0:3], v[146:149], v[122:137]
	s_waitcnt lgkmcnt(0)
	v_mfma_f32_32x32x16_bf16 v[106:121], v[4:7], v[146:149], v[106:121]
	ds_read_b128 v[0:3], v232 offset:49280
	ds_read_b128 v[4:7], v232 offset:57472
	s_waitcnt lgkmcnt(1)
	v_mfma_f32_32x32x16_bf16 v[122:137], v[0:3], v[142:145], v[122:137]
	s_waitcnt lgkmcnt(0)
	v_mfma_f32_32x32x16_bf16 v[106:121], v[4:7], v[142:145], v[106:121]
	ds_read_b128 v[0:3], v233 offset:49280
	ds_read_b128 v[4:7], v233 offset:57472
	s_waitcnt lgkmcnt(1)
	v_mfma_f32_32x32x16_bf16 v[122:137], v[0:3], v[138:141], v[122:137]
	v_exp_f32_e32 v0, v90
	v_exp_f32_e32 v1, v91
	v_exp_f32_e32 v2, v92
	v_exp_f32_e32 v3, v93
	v_exp_f32_e32 v90, v98
	v_add_f32_e32 v98, 0, v0
	v_add_f32_e32 v98, v1, v98
	s_waitcnt lgkmcnt(0)
	v_mfma_f32_32x32x16_bf16 v[106:121], v[4:7], v[138:141], v[106:121]
	v_exp_f32_e32 v4, v94
	v_exp_f32_e32 v5, v95
	v_exp_f32_e32 v6, v96
	v_add_f32_e32 v98, v2, v98
	v_exp_f32_e32 v7, v97
	v_add_f32_e32 v98, v3, v98
	v_add_f32_e32 v98, v4, v98
	v_exp_f32_e32 v91, v99
	v_add_f32_e32 v98, v5, v98
	v_exp_f32_e32 v92, v100
	v_add_f32_e32 v98, v6, v98
	v_exp_f32_e32 v93, v101
	v_add_f32_e32 v98, v7, v98
	v_exp_f32_e32 v94, v102
	v_add_f32_e32 v98, v90, v98
	v_exp_f32_e32 v95, v103
	v_add_f32_e32 v98, v91, v98
	v_exp_f32_e32 v96, v104
	v_add_f32_e32 v98, v92, v98
	v_exp_f32_e32 v97, v105
	v_add_f32_e32 v98, v93, v98
	v_add_f32_e32 v98, v94, v98
	v_add_f32_e32 v98, v95, v98
	v_add_f32_e32 v98, v96, v98
	v_add_f32_e32 v98, v97, v98
	v_add_f32_e32 v98, v74, v98
	v_add_f32_e32 v98, v75, v98
	v_add_f32_e32 v98, v76, v98
	v_add_f32_e32 v98, v77, v98
	v_add_f32_e32 v98, v78, v98
	v_add_f32_e32 v98, v79, v98
	v_add_f32_e32 v98, v80, v98
	v_add_f32_e32 v98, v81, v98
	v_add_f32_e32 v98, v82, v98
	v_add_f32_e32 v98, v83, v98
	v_add_f32_e32 v98, v84, v98
	v_add_f32_e32 v98, v85, v98
	v_add_f32_e32 v98, v86, v98
	v_add_f32_e32 v98, v87, v98
	v_add_f32_e32 v98, v88, v98
	v_add_f32_e32 v234, v89, v98
	v_mov_b32_e32 v235, v234
	v_cvt_pk_bf16_f32 v0, v0, v1
	v_cvt_pk_bf16_f32 v1, v2, v3
	v_cvt_pk_bf16_f32 v2, v4, v5
	v_cvt_pk_bf16_f32 v3, v6, v7
	v_cvt_pk_bf16_f32 v4, v90, v91
	v_cvt_pk_bf16_f32 v5, v92, v93
	v_cvt_pk_bf16_f32 v6, v94, v95
	v_cvt_pk_bf16_f32 v7, v96, v97
	v_cvt_pk_bf16_f32 v74, v74, v75
	v_cvt_pk_bf16_f32 v75, v76, v77
	v_cvt_pk_bf16_f32 v76, v78, v79
	v_cvt_pk_bf16_f32 v77, v80, v81
	v_cvt_pk_bf16_f32 v78, v82, v83
	v_cvt_pk_bf16_f32 v79, v84, v85
	v_cvt_pk_bf16_f32 v80, v86, v87
	v_cvt_pk_bf16_f32 v81, v88, v89
	s_nop 1
	v_permlane32_swap_b32_e32 v234, v235
	v_permlane32_swap_b32_e32 v0, v2
	v_permlane32_swap_b32_e32 v74, v76
	v_permlane32_swap_b32_e32 v75, v77
	v_permlane32_swap_b32_e32 v78, v80
	v_permlane32_swap_b32_e32 v79, v81
	v_permlane32_swap_b32_e32 v1, v3
	v_permlane32_swap_b32_e32 v4, v6
	v_permlane32_swap_b32_e32 v5, v7
	s_add_i32 s9, s6, s3
	s_add_i32 s10, s9, 1
	s_ashr_i32 s11, s10, 31
	s_lshl_b64 s[10:11], s[10:11], 18
	s_add_u32 s92, s89, s10
	s_addc_u32 s93, s24, s11
	s_add_u32 s10, s0, s10
	s_addc_u32 s11, s25, s11
	s_cmp_lt_i32 s4, s30
	s_cselect_b64 vcc, -1, 0
	s_and_b64 s[4:5], vcc, exec
	s_cselect_b32 s5, s93, s1
	s_cselect_b32 s4, s92, s16
	s_cselect_b32 s11, s11, s29
	s_cselect_b32 s10, s10, s28
	s_waitcnt lgkmcnt(0)
; #define PV_WAIT4() do { asm volatile("s_waitcnt lgkmcnt(4)" ::: "memory"); SBAR(); } while (0)
; #define PV_WAIT0() do { asm volatile("s_waitcnt lgkmcnt(0)" ::: "memory"); SBAR(); } while (0)
; #define PV_MM(od, pX, pY, g) do { od = __builtin_amdgcn_mfma_f32_32x32x16_bf16(pX, PK(g.l0, g.h0), od, 0, 0, 0); od = __builtin_amdgcn_mfma_f32_32x32x16_bf16(pY, PK(g.l1, g.h1), od, 0, 0, 0); } while (0)
; template <int MODE>
; __device__ __forceinline__ void qkt(f32x16& p0, f32x16& p1, const bf16* Ks, const bf16x8* qr, int r32, int hi, float dq, float nsl, int side, float mi) {
;   if (MODE == 0) {
;     if (side != 0) {
;       const float sg = side > 0 ? -nsl : nsl, bb = -sg * dq - mi;
; #pragma unroll
;       for (int r = 0; r < 16; ++r) { const float c = (float)((r & 3) + 8 * (r >> 2)); p0[r] = fmaf(c, sg, bb); p1[r] = fmaf(c + 32.f, sg, bb); }
;     } else {
; #pragma unroll
;       for (int r = 0; r < 16; ++r) { const float c = (float)((r & 3) + 8 * (r >> 2)); p0[r] = fmaf(fabsf(dq - c), nsl, -mi); p1[r] = fmaf(fabsf(dq - (c + 32.f)), nsl, -mi); }
;     }
; __device__ __forceinline__ void pv_d0(f32x16* o, int vb, bf16x8 pa0, bf16x8 pa1, bf16x8 pa2, bf16x8 pa3) {
;   asm volatile("s_waitcnt lgkmcnt(0)" ::: "memory");
;   VG a0 = pv_reads<0, 0>(vb), b0 = pv_reads<0, 2>(vb);
;   PV_WAIT4(); PV_MM(o[0], pa0, pa1, a0); VG a1 = pv_reads<1, 0>(vb);
;   PV_WAIT4(); PV_MM(o[0], pa2, pa3, b0); VG b1 = pv_reads<1, 2>(vb);
;   PV_WAIT4(); PV_MM(o[1], pa0, pa1, a1); VG a2 = pv_reads<2, 0>(vb);
;   PV_WAIT4(); PV_MM(o[1], pa2, pa3, b1); VG b2 = pv_reads<2, 2>(vb);
;   PV_WAIT4(); PV_MM(o[2], pa0, pa1, a2); VG a3 = pv_reads<3, 0>(vb);
;   PV_WAIT4(); PV_MM(o[2], pa2, pa3, b2); VG b3 = pv_reads<3, 2>(vb);
;   PV_WAIT4(); PV_MM(o[3], pa0, pa1, a3);
;   PV_WAIT0(); PV_MM(o[3], pa2, pa3, b3);
; }
	ds_read_b64_tr_b16 v[98:99], v220 offset:0
	ds_read_b64_tr_b16 v[100:101], v220 offset:0x800
	ds_read_b64_tr_b16 v[102:103], v220 offset:0x1000
	ds_read_b64_tr_b16 v[104:105], v220 offset:0x1800
	ds_read_b64_tr_b16 v[236:237], v220 offset:0x2000
	ds_read_b64_tr_b16 v[238:239], v220 offset:0x2800
	ds_read_b64_tr_b16 v[240:241], v220 offset:0x3000
	ds_read_b64_tr_b16 v[242:243], v220 offset:0x3800
	s_waitcnt lgkmcnt(4)
	s_nop 0
	v_mfma_f32_32x32x16_bf16 v[58:73], v[0:3], v[98:101], v[58:73]
	ds_read_b64_tr_b16 v[98:99], v220 offset:0x200
	ds_read_b64_tr_b16 v[100:101], v220 offset:0xa00
	v_mfma_f32_32x32x16_bf16 v[58:73], v[4:7], v[102:105], v[58:73]
	ds_read_b64_tr_b16 v[102:103], v220 offset:0x1200
	ds_read_b64_tr_b16 v[104:105], v220 offset:0x1a00
	s_waitcnt lgkmcnt(4)
	v_mfma_f32_32x32x16_bf16 v[58:73], v[74:77], v[236:239], v[58:73]
	ds_read_b64_tr_b16 v[236:237], v220 offset:0x2200
	ds_read_b64_tr_b16 v[238:239], v220 offset:0x2a00
	v_mfma_f32_32x32x16_bf16 v[58:73], v[78:81], v[240:243], v[58:73]
	ds_read_b64_tr_b16 v[240:241], v220 offset:0x3200
	ds_read_b64_tr_b16 v[242:243], v220 offset:0x3a00
	s_waitcnt lgkmcnt(4)
	v_mfma_f32_32x32x16_bf16 v[42:57], v[0:3], v[98:101], v[42:57]
	ds_read_b64_tr_b16 v[98:99], v220 offset:0x400
	ds_read_b64_tr_b16 v[100:101], v220 offset:0xc00
	v_mfma_f32_32x32x16_bf16 v[42:57], v[4:7], v[102:105], v[42:57]
	ds_read_b64_tr_b16 v[102:103], v220 offset:0x1400
	ds_read_b64_tr_b16 v[104:105], v220 offset:0x1c00
	s_waitcnt lgkmcnt(4)
	v_mfma_f32_32x32x16_bf16 v[42:57], v[74:77], v[236:239], v[42:57]
	ds_read_b64_tr_b16 v[236:237], v220 offset:0x2400
	ds_read_b64_tr_b16 v[238:239], v220 offset:0x2c00
	v_mfma_f32_32x32x16_bf16 v[42:57], v[78:81], v[240:243], v[42:57]
	ds_read_b64_tr_b16 v[240:241], v220 offset:0x3400
	ds_read_b64_tr_b16 v[242:243], v220 offset:0x3c00
	s_waitcnt lgkmcnt(4)
	v_mfma_f32_32x32x16_bf16 v[26:41], v[0:3], v[98:101], v[26:41]
	ds_read_b64_tr_b16 v[98:99], v220 offset:0x600
	ds_read_b64_tr_b16 v[100:101], v220 offset:0xe00
	v_mfma_f32_32x32x16_bf16 v[26:41], v[4:7], v[102:105], v[26:41]
	ds_read_b64_tr_b16 v[102:103], v220 offset:0x1600
	ds_read_b64_tr_b16 v[104:105], v220 offset:0x1e00
	s_waitcnt lgkmcnt(4)
	v_mfma_f32_32x32x16_bf16 v[26:41], v[74:77], v[236:239], v[26:41]
	ds_read_b64_tr_b16 v[236:237], v220 offset:0x2600
	ds_read_b64_tr_b16 v[238:239], v220 offset:0x2e00
	v_mfma_f32_32x32x16_bf16 v[26:41], v[78:81], v[240:243], v[26:41]
	ds_read_b64_tr_b16 v[240:241], v220 offset:0x3600
	ds_read_b64_tr_b16 v[242:243], v220 offset:0x3e00
	s_waitcnt lgkmcnt(4)
	v_mfma_f32_32x32x16_bf16 v[10:25], v[0:3], v[98:101], v[10:25]
	s_waitcnt lgkmcnt(0)
	v_mfma_f32_32x32x16_bf16 v[10:25], v[4:7], v[102:105], v[10:25]
	v_mfma_f32_32x32x16_bf16 v[10:25], v[74:77], v[236:239], v[10:25]
	v_mfma_f32_32x32x16_bf16 v[10:25], v[78:81], v[240:243], v[10:25]
	s_waitcnt vmcnt(0)
	s_barrier
	s_cselect_b32 s4, s31, 0x10000000
	s_add_i32 s5, s4, s13
	v_cvt_f32_i32_e32 v0, s91
	s_cmp_lt_i32 s5, 63
	s_cselect_b64 s[10:11], -1, 0
	s_add_i32 s4, s4, s23
	s_cmp_gt_i32 s4, 0
	s_cselect_b64 s[4:5], -1, 0
	v_cndmask_b32_e32 v0, v214, v0, vcc
	s_and_b64 s[4:5], s[10:11], s[4:5]
	v_sub_f32_e32 v0, v176, v0
	s_andn2_b64 vcc, exec, s[4:5]
	s_mov_b64 s[4:5], -1
	s_cbranch_vccz .LBB0_699
	v_cndmask_b32_e64 v2, -v172, v172, s[10:11]
	v_fma_f32 v4, v0, -v2, -v174
	v_fma_f32 v90, 0, v2, v4
	v_add_f32_e32 v91, v2, v4
	v_pk_fma_f32 v[74:75], v[2:3], s[34:35], v[4:5] op_sel_hi:[0,1,0]
	v_pk_fma_f32 v[92:93], v[2:3], s[36:37], v[4:5] op_sel_hi:[0,1,0]
	v_pk_fma_f32 v[76:77], v[2:3], s[38:39], v[4:5] op_sel_hi:[0,1,0]
	v_pk_fma_f32 v[94:95], v[2:3], s[40:41], v[4:5] op_sel_hi:[0,1,0]
	v_pk_fma_f32 v[78:79], v[2:3], s[42:43], v[4:5] op_sel_hi:[0,1,0]
	v_pk_fma_f32 v[96:97], v[2:3], s[44:45], v[4:5] op_sel_hi:[0,1,0]
	v_pk_fma_f32 v[80:81], v[2:3], s[46:47], v[4:5] op_sel_hi:[0,1,0]
	v_pk_fma_f32 v[98:99], v[2:3], s[48:49], v[4:5] op_sel_hi:[0,1,0]
	v_pk_fma_f32 v[82:83], v[2:3], s[50:51], v[4:5] op_sel_hi:[0,1,0]
	v_pk_fma_f32 v[100:101], v[2:3], s[52:53], v[4:5] op_sel_hi:[0,1,0]
	v_pk_fma_f32 v[84:85], v[2:3], s[54:55], v[4:5] op_sel_hi:[0,1,0]
	v_pk_fma_f32 v[102:103], v[2:3], s[56:57], v[4:5] op_sel_hi:[0,1,0]
	v_pk_fma_f32 v[86:87], v[2:3], s[58:59], v[4:5] op_sel_hi:[0,1,0]
	v_fmamk_f32 v88, v2, 0x42680000, v4
	v_pk_fma_f32 v[104:105], v[2:3], s[60:61], v[4:5] op_sel_hi:[0,1,0]
	v_fmac_f32_e32 v4, 0x426c0000, v2
	s_mov_b64 s[4:5], 0
	v_mov_b32_e32 v89, v4

; __device__ __forceinline__ void finishSM(f32x16& p0, f32x16& p1, float& l_reg, bf16x8& pa0, bf16x8& pa1, bf16x8& pa2, bf16x8& pa3) {
; #pragma unroll
;   for (int r = 0; r < 16; ++r) p0[r] = __builtin_amdgcn_exp2f(p0[r]);
; #pragma unroll
;   for (int r = 0; r < 16; ++r) p1[r] = __builtin_amdgcn_exp2f(p1[r]);
;   float ps = 0;
; #pragma unroll
;   for (int r = 0; r < 16; ++r) ps += p0[r];
; #pragma unroll
;   for (int r = 0; r < 16; ++r) ps += p1[r];
;   { auto rr = __builtin_amdgcn_permlane32_swap(__float_as_uint(ps), __float_as_uint(ps), false, false);
;     ps = __uint_as_float(rr[0]) + __uint_as_float(rr[1]); }
;   l_reg += ps;
;     ...
;   PK4(p0, 0, pa0); PK4(p0, 8, pa1); PK4(p1, 0, pa2); PK4(p1, 8, pa3);
;     ...
; }
; template <int MODE>
; __device__ __forceinline__ void qkt(f32x16& p0, f32x16& p1, const bf16* Ks, const bf16x8* qr, int r32, int hi, float dq, float nsl, int side, float mi) {
;   if (MODE == 0) {
;     if (side != 0) {
;       const float sg = side > 0 ? -nsl : nsl, bb = -sg * dq - mi;
; #pragma unroll
;       for (int r = 0; r < 16; ++r) { const float c = (float)((r & 3) + 8 * (r >> 2)); p0[r] = fmaf(c, sg, bb); p1[r] = fmaf(c + 32.f, sg, bb); }
;     } else {
; #pragma unroll
;       for (int r = 0; r < 16; ++r) { const float c = (float)((r & 3) + 8 * (r >> 2)); p0[r] = fmaf(fabsf(dq - c), nsl, -mi); p1[r] = fmaf(fabsf(dq - (c + 32.f)), nsl, -mi); }
;     }
;   } else {
; #pragma unroll
;     for (int r = 0; r < 16; ++r) { const float c = (float)((r & 3) + 8 * (r >> 2)); p0[r] = (r < 8) ? fmaf(fabsf(dq - c), nsl, -mi) : NEGBIG; p1[r] = NEGBIG; }
;   }
; #pragma unroll
;   for (int d0 = 0; d0 < 8; ++d0) {
;     const int ko = r32 * 256 + ((((d0 & 3) * 32 + hi * 16) ^ ((r32 & 7) << 4))) + (d0 >> 2) * 128;
;     bf16x8 b0 = *reinterpret_cast<const bf16x8*>((const char*)Ks + ko);
;     bf16x8 b1 = *reinterpret_cast<const bf16x8*>((const char*)Ks + ko + 8192);
;     p0 = __builtin_amdgcn_mfma_f32_32x32x16_bf16(b0, qr[d0], p0, 0, 0, 0);
;     p1 = __builtin_amdgcn_mfma_f32_32x32x16_bf16(b1, qr[d0], p1, 0, 0, 0); }
; template <int J> ...
;     ...
;     SBAR(); qkt<0>(pA0, pA1, K_lds, qr, r32, hi, TILE_DQ(j + 1), nsl, TILE_SIDE(j + 1), mi);
;     finishSM(pB0, pB1, l_reg, pa0, pa1, pa2, pa3); SBAR();
;     if (SDEPTH == 1 || j + 3 < NT) SLOAD(SE, j + 1 + SDEPTH); SBAR();
;     pv_d0(o, vb0 + (int)SHM_V, pa0, pa1, pa2, pa3); SBAR();
.LBB0_701:
	v_readfirstlane_b32 s92, v248
	s_add_i32 s4, s6, s3
	s_add_i32 s10, s4, 2
	s_ashr_i32 s11, s10, 31
	s_lshl_b64 s[10:11], s[10:11], 18
	s_add_u32 s10, s89, s10
	s_addc_u32 s11, s24, s11
	s_add_i32 s5, s3, 2
	s_cmp_lt_i32 s5, s30
	s_cselect_b32 s10, s10, s16
	s_cselect_b32 s11, s11, s1
	s_add_i32 s4, s4, 1
	s_ashr_i32 s5, s4, 31
	s_lshl_b64 s[4:5], s[4:5], 18
	s_add_u32 s4, s0, s4
	s_addc_u32 s5, s25, s5
	s_add_i32 m0, s92, 0xc000
	s_nop 0
	global_load_lds_dwordx4 v245, s[10:11]
	s_add_i32 m0, s92, 0xc400
	s_nop 0
	global_load_lds_dwordx4 v246, s[10:11]
	s_add_i32 m0, s92, 0x0
	s_nop 0
	global_load_lds_dwordx4 v247, s[4:5]
	s_add_i32 m0, s92, 0x380
	s_nop 0
	global_load_lds_dwordx4 v247, s[4:5] offset:128
	v_add_f32_e32 v0, v234, v235
	v_add_f32_e32 v173, v227, v0
	ds_read_b128 v[0:3], v230 offset:32768
	ds_read_b128 v[4:7], v230 offset:40960
	v_exp_f32_e32 v106, v106
	v_exp_f32_e32 v107, v107
	s_waitcnt lgkmcnt(1)
	v_mfma_f32_32x32x16_bf16 v[90:105], v[0:3], v[166:169], v[90:105]
	v_exp_f32_e32 v108, v108
	v_exp_f32_e32 v109, v109
	v_exp_f32_e32 v110, v110
	v_exp_f32_e32 v111, v111
	v_exp_f32_e32 v112, v112
	v_exp_f32_e32 v113, v113
	v_exp_f32_e32 v114, v114
	s_waitcnt lgkmcnt(0)
	v_mfma_f32_32x32x16_bf16 v[74:89], v[4:7], v[166:169], v[74:89]
	ds_read_b128 v[0:3], v231 offset:32768
	ds_read_b128 v[4:7], v231 offset:40960
	v_exp_f32_e32 v115, v115
	v_exp_f32_e32 v116, v116
	v_exp_f32_e32 v117, v117
	v_exp_f32_e32 v118, v118
	v_exp_f32_e32 v119, v119
	v_exp_f32_e32 v120, v120
	s_waitcnt lgkmcnt(1)
	v_mfma_f32_32x32x16_bf16 v[90:105], v[0:3], v[162:165], v[90:105]
	v_exp_f32_e32 v121, v121
	s_waitcnt lgkmcnt(0)
	v_mfma_f32_32x32x16_bf16 v[74:89], v[4:7], v[162:165], v[74:89]
	ds_read_b128 v[0:3], v232 offset:32768
	ds_read_b128 v[4:7], v232 offset:40960
	s_waitcnt lgkmcnt(1)
	v_mfma_f32_32x32x16_bf16 v[90:105], v[0:3], v[158:161], v[90:105]
	s_waitcnt lgkmcnt(0)
	v_mfma_f32_32x32x16_bf16 v[74:89], v[4:7], v[158:161], v[74:89]
	ds_read_b128 v[0:3], v233 offset:32768
	ds_read_b128 v[4:7], v233 offset:40960
	s_waitcnt lgkmcnt(1)
	v_mfma_f32_32x32x16_bf16 v[90:105], v[0:3], v[154:157], v[90:105]
	s_waitcnt lgkmcnt(0)
	v_mfma_f32_32x32x16_bf16 v[74:89], v[4:7], v[154:157], v[74:89]
	ds_read_b128 v[0:3], v230 offset:32896
	ds_read_b128 v[4:7], v230 offset:41088
	s_waitcnt lgkmcnt(1)
	v_mfma_f32_32x32x16_bf16 v[90:105], v[0:3], v[150:153], v[90:105]
	s_waitcnt lgkmcnt(0)
	v_mfma_f32_32x32x16_bf16 v[74:89], v[4:7], v[150:153], v[74:89]
	ds_read_b128 v[0:3], v231 offset:32896
	ds_read_b128 v[4:7], v231 offset:41088
	s_waitcnt lgkmcnt(1)
	v_mfma_f32_32x32x16_bf16 v[90:105], v[0:3], v[146:149], v[90:105]
	s_waitcnt lgkmcnt(0)
	v_mfma_f32_32x32x16_bf16 v[74:89], v[4:7], v[146:149], v[74:89]
	ds_read_b128 v[0:3], v232 offset:32896
	ds_read_b128 v[4:7], v232 offset:41088
	s_waitcnt lgkmcnt(1)
	v_mfma_f32_32x32x16_bf16 v[90:105], v[0:3], v[142:145], v[90:105]
	s_waitcnt lgkmcnt(0)
	v_mfma_f32_32x32x16_bf16 v[74:89], v[4:7], v[142:145], v[74:89]
	ds_read_b128 v[0:3], v233 offset:32896
	ds_read_b128 v[4:7], v233 offset:41088
	s_waitcnt lgkmcnt(1)
	v_mfma_f32_32x32x16_bf16 v[90:105], v[0:3], v[138:141], v[90:105]
	v_exp_f32_e32 v0, v122
	v_exp_f32_e32 v1, v123
	v_exp_f32_e32 v2, v124
	v_exp_f32_e32 v3, v125
	v_exp_f32_e32 v122, v130
	v_add_f32_e32 v130, 0, v0
	v_add_f32_e32 v130, v1, v130
	s_waitcnt lgkmcnt(0)
	v_mfma_f32_32x32x16_bf16 v[74:89], v[4:7], v[138:141], v[74:89]
	v_exp_f32_e32 v4, v126
	v_exp_f32_e32 v5, v127
	v_exp_f32_e32 v6, v128
	v_add_f32_e32 v130, v2, v130
	v_exp_f32_e32 v7, v129
	v_add_f32_e32 v130, v3, v130
	v_add_f32_e32 v130, v4, v130
	v_exp_f32_e32 v123, v131
	v_add_f32_e32 v130, v5, v130
	v_exp_f32_e32 v124, v132
	v_add_f32_e32 v130, v6, v130
	v_exp_f32_e32 v125, v133
	v_add_f32_e32 v130, v7, v130
	v_exp_f32_e32 v126, v134
	v_add_f32_e32 v130, v122, v130
	v_exp_f32_e32 v127, v135
	v_add_f32_e32 v130, v123, v130
	v_exp_f32_e32 v128, v136
	v_add_f32_e32 v130, v124, v130
	v_exp_f32_e32 v129, v137
	v_add_f32_e32 v130, v125, v130
	v_add_f32_e32 v130, v126, v130
	v_add_f32_e32 v130, v127, v130
	v_add_f32_e32 v130, v128, v130
	v_add_f32_e32 v130, v129, v130
	v_add_f32_e32 v130, v106, v130
	v_add_f32_e32 v130, v107, v130
	v_add_f32_e32 v130, v108, v130
	v_add_f32_e32 v130, v109, v130
	v_add_f32_e32 v130, v110, v130
	v_add_f32_e32 v130, v111, v130
	v_add_f32_e32 v130, v112, v130
	v_add_f32_e32 v130, v113, v130
	v_add_f32_e32 v130, v114, v130
	v_add_f32_e32 v130, v115, v130
	v_add_f32_e32 v130, v116, v130
	v_add_f32_e32 v130, v117, v130
	v_add_f32_e32 v130, v118, v130
	v_add_f32_e32 v130, v119, v130
	v_add_f32_e32 v130, v120, v130
	v_add_f32_e32 v130, v121, v130
	v_mov_b32_e32 v131, v130
	s_nop 1
	v_permlane32_swap_b32_e32 v130, v131
	v_add_f32_e32 v130, v130, v131
	v_add_f32_e32 v227, v173, v130
	v_cvt_pk_bf16_f32 v0, v0, v1
	v_cvt_pk_bf16_f32 v1, v2, v3
	v_cvt_pk_bf16_f32 v2, v4, v5
	v_cvt_pk_bf16_f32 v3, v6, v7
	v_cvt_pk_bf16_f32 v4, v122, v123
	v_cvt_pk_bf16_f32 v5, v124, v125
	v_cvt_pk_bf16_f32 v6, v126, v127
	v_cvt_pk_bf16_f32 v7, v128, v129
	v_cvt_pk_bf16_f32 v106, v106, v107
	v_cvt_pk_bf16_f32 v107, v108, v109
	v_cvt_pk_bf16_f32 v108, v110, v111
	v_cvt_pk_bf16_f32 v109, v112, v113
	v_cvt_pk_bf16_f32 v110, v114, v115
	v_cvt_pk_bf16_f32 v111, v116, v117
	v_cvt_pk_bf16_f32 v112, v118, v119
	v_cvt_pk_bf16_f32 v113, v120, v121
	s_nop 0
	v_permlane32_swap_b32_e32 v0, v2
	v_permlane32_swap_b32_e32 v1, v3
	v_permlane32_swap_b32_e32 v4, v6
	v_permlane32_swap_b32_e32 v5, v7
	v_permlane32_swap_b32_e32 v106, v108
	v_permlane32_swap_b32_e32 v107, v109
	v_permlane32_swap_b32_e32 v110, v112
	v_permlane32_swap_b32_e32 v111, v113
	s_add_i32 s10, s9, 2
	s_ashr_i32 s11, s10, 31
	s_add_i32 s4, s3, 2
	s_lshl_b64 s[10:11], s[10:11], 18
	s_add_u32 s5, s89, s10
	s_addc_u32 s9, s24, s11
	s_add_u32 s92, s0, s10
	s_addc_u32 s93, s25, s11
	s_cmp_lt_i32 s4, s30
	s_cselect_b32 s11, s9, s1
	s_cselect_b32 s10, s5, s16
	s_cselect_b32 s93, s93, s29
	s_cselect_b32 s92, s92, s28
	s_waitcnt lgkmcnt(0)
; #define SBAR() __builtin_amdgcn_sched_barrier(0)
; #define PV_WAIT4() do { asm volatile("s_waitcnt lgkmcnt(4)" ::: "memory"); SBAR(); } while (0)
; #define PV_WAIT0() do { asm volatile("s_waitcnt lgkmcnt(0)" ::: "memory"); SBAR(); } while (0)
; #define PV_MM(od, pX, pY, g) do { od = __builtin_amdgcn_mfma_f32_32x32x16_bf16(pX, PK(g.l0, g.h0), od, 0, 0, 0); od = __builtin_amdgcn_mfma_f32_32x32x16_bf16(pY, PK(g.l1, g.h1), od, 0, 0, 0); } while (0)
; #define SWRITE(b, i) do { *(bf16x8*)((char*)V_lds + (b) * SHM_V + vst0) = sr_[i].vs0;          \
;     *(bf16x8*)((char*)V_lds + (b) * SHM_V + vst1) = sr_[i].vs1; int kc = sc * 2;               \
;     *(bf16x8*)((char*)K_lds + (b) * SHM_K + KSWZ(sr, kc)) = sr_[i].ks0;                       \
;     *(bf16x8*)((char*)K_lds + (b) * SHM_K + KSWZ(32 + sr, kc)) = sr_[i].ks1; } while (0)
; #define SWAIT() do { if constexpr (SDEPTH == 2) asm volatile("s_waitcnt vmcnt(4)" ::: "memory"); else asm volatile("s_waitcnt vmcnt(0)" ::: "memory"); } while (0)
; __device__ __forceinline__ void pv_d0(f32x16* o, int vb, bf16x8 pa0, bf16x8 pa1, bf16x8 pa2, bf16x8 pa3) {
;   asm volatile("s_waitcnt lgkmcnt(0)" ::: "memory");
;   VG a0 = pv_reads<0, 0>(vb), b0 = pv_reads<0, 2>(vb);
;   PV_WAIT4(); PV_MM(o[0], pa0, pa1, a0); VG a1 = pv_reads<1, 0>(vb);
;   PV_WAIT4(); PV_MM(o[0], pa2, pa3, b0); VG b1 = pv_reads<1, 2>(vb);
;   PV_WAIT4(); PV_MM(o[1], pa0, pa1, a1); VG a2 = pv_reads<2, 0>(vb);
;   PV_WAIT4(); PV_MM(o[1], pa2, pa3, b1); VG b2 = pv_reads<2, 2>(vb);
;   PV_WAIT4(); PV_MM(o[2], pa0, pa1, a2); VG a3 = pv_reads<3, 0>(vb);
;   PV_WAIT4(); PV_MM(o[2], pa2, pa3, b2); VG b3 = pv_reads<3, 2>(vb);
;   PV_WAIT4(); PV_MM(o[3], pa0, pa1, a3);
;   PV_WAIT0(); PV_MM(o[3], pa2, pa3, b3);
; }
; template <int J> ...
;     ...
;     pv_d0(o, vb0 + (int)SHM_V, pa0, pa1, pa2, pa3); SBAR();
;     __syncthreads(); SWAIT(); SWRITE(1, SO);
;     __syncthreads();
;   }
	ds_read_b64_tr_b16 v[130:131], v229 offset:0
	ds_read_b64_tr_b16 v[132:133], v229 offset:0x800
	ds_read_b64_tr_b16 v[134:135], v229 offset:0x1000
	ds_read_b64_tr_b16 v[136:137], v229 offset:0x1800
	ds_read_b64_tr_b16 v[234:235], v229 offset:0x2000
	ds_read_b64_tr_b16 v[236:237], v229 offset:0x2800
	ds_read_b64_tr_b16 v[238:239], v229 offset:0x3000
	ds_read_b64_tr_b16 v[240:241], v229 offset:0x3800
	s_waitcnt lgkmcnt(4)
	s_nop 0
	v_mfma_f32_32x32x16_bf16 v[58:73], v[0:3], v[130:133], v[58:73]
	ds_read_b64_tr_b16 v[130:131], v229 offset:0x200
	ds_read_b64_tr_b16 v[132:133], v229 offset:0xa00
	v_mfma_f32_32x32x16_bf16 v[58:73], v[4:7], v[134:137], v[58:73]
	ds_read_b64_tr_b16 v[134:135], v229 offset:0x1200
	ds_read_b64_tr_b16 v[136:137], v229 offset:0x1a00
	s_waitcnt lgkmcnt(4)
	v_mfma_f32_32x32x16_bf16 v[58:73], v[106:109], v[234:237], v[58:73]
	ds_read_b64_tr_b16 v[234:235], v229 offset:0x2200
	ds_read_b64_tr_b16 v[236:237], v229 offset:0x2a00
	v_mfma_f32_32x32x16_bf16 v[58:73], v[110:113], v[238:241], v[58:73]
	ds_read_b64_tr_b16 v[238:239], v229 offset:0x3200
	ds_read_b64_tr_b16 v[240:241], v229 offset:0x3a00
	s_waitcnt lgkmcnt(4)
	v_mfma_f32_32x32x16_bf16 v[42:57], v[0:3], v[130:133], v[42:57]
	ds_read_b64_tr_b16 v[130:131], v229 offset:0x400
	ds_read_b64_tr_b16 v[132:133], v229 offset:0xc00
	v_mfma_f32_32x32x16_bf16 v[42:57], v[4:7], v[134:137], v[42:57]
	ds_read_b64_tr_b16 v[134:135], v229 offset:0x1400
	ds_read_b64_tr_b16 v[136:137], v229 offset:0x1c00
	s_waitcnt lgkmcnt(4)
	v_mfma_f32_32x32x16_bf16 v[42:57], v[106:109], v[234:237], v[42:57]
	ds_read_b64_tr_b16 v[234:235], v229 offset:0x2400
	ds_read_b64_tr_b16 v[236:237], v229 offset:0x2c00
	v_mfma_f32_32x32x16_bf16 v[42:57], v[110:113], v[238:241], v[42:57]
	ds_read_b64_tr_b16 v[238:239], v229 offset:0x3400
	ds_read_b64_tr_b16 v[240:241], v229 offset:0x3c00
	s_waitcnt lgkmcnt(4)
	v_mfma_f32_32x32x16_bf16 v[26:41], v[0:3], v[130:133], v[26:41]
	ds_read_b64_tr_b16 v[130:131], v229 offset:0x600
	ds_read_b64_tr_b16 v[132:133], v229 offset:0xe00
	v_mfma_f32_32x32x16_bf16 v[26:41], v[4:7], v[134:137], v[26:41]
	ds_read_b64_tr_b16 v[134:135], v229 offset:0x1600
	ds_read_b64_tr_b16 v[136:137], v229 offset:0x1e00
	s_waitcnt lgkmcnt(4)
	v_mfma_f32_32x32x16_bf16 v[26:41], v[106:109], v[234:237], v[26:41]
	ds_read_b64_tr_b16 v[234:235], v229 offset:0x2600
	ds_read_b64_tr_b16 v[236:237], v229 offset:0x2e00
	v_mfma_f32_32x32x16_bf16 v[26:41], v[110:113], v[238:241], v[26:41]
	ds_read_b64_tr_b16 v[238:239], v229 offset:0x3600
	ds_read_b64_tr_b16 v[240:241], v229 offset:0x3e00
	s_waitcnt lgkmcnt(4)
	v_mfma_f32_32x32x16_bf16 v[10:25], v[0:3], v[130:133], v[10:25]
	s_waitcnt lgkmcnt(0)
	v_mfma_f32_32x32x16_bf16 v[10:25], v[4:7], v[134:137], v[10:25]
	v_mfma_f32_32x32x16_bf16 v[10:25], v[106:109], v[234:237], v[10:25]
	v_mfma_f32_32x32x16_bf16 v[10:25], v[110:113], v[238:241], v[10:25]
	s_addk_i32 s31, 0xff80
	s_addk_i32 s91, 0x80
	s_add_i32 s3, s3, 3
	s_cmp_ge_i32 s3, s7
	s_waitcnt vmcnt(0)
	s_barrier
	s_cbranch_scc1 .Lmy_i1_exit
	s_mov_b32 s3, s4
	s_branch .LBB0_693
.Lmy_i1_exit:
	v_readfirstlane_b32 s92, v248
	s_add_i32 s4, s6, s7
	s_add_i32 s4, s4, -1
	s_ashr_i32 s5, s4, 31
	s_lshl_b64 s[4:5], s[4:5], 18
	s_add_u32 s4, s0, s4
	s_addc_u32 s5, s25, s5
	s_cmp_gt_i32 s7, s30
	s_cselect_b32 s4, s28, s4
	s_cselect_b32 s5, s29, s5
	s_add_i32 m0, s92, 0x4000
	s_nop 0
	global_load_lds_dwordx4 v247, s[4:5]
	s_add_i32 m0, s92, 0x4380
	s_nop 0
	global_load_lds_dwordx4 v247, s[4:5] offset:128
	s_branch .LBB0_704

; #define SBAR() __builtin_amdgcn_sched_barrier(0)
; __device__ __forceinline__ void finishSM(f32x16& p0, f32x16& p1, float& l_reg, bf16x8& pa0, bf16x8& pa1, bf16x8& pa2, bf16x8& pa3) {
; #pragma unroll
;   for (int r = 0; r < 16; ++r) p0[r] = __builtin_amdgcn_exp2f(p0[r]);
; #pragma unroll
;   for (int r = 0; r < 16; ++r) p1[r] = __builtin_amdgcn_exp2f(p1[r]);
;   float ps = 0;
; #pragma unroll
;   for (int r = 0; r < 16; ++r) ps += p0[r];
; #pragma unroll
;   for (int r = 0; r < 16; ++r) ps += p1[r];
;   { auto rr = __builtin_amdgcn_permlane32_swap(__float_as_uint(ps), __float_as_uint(ps), false, false);
;     ps = __uint_as_float(rr[0]) + __uint_as_float(rr[1]); }
;   l_reg += ps;
;     ...
;   PK4(p0, 0, pa0); PK4(p0, 8, pa1); PK4(p1, 0, pa2); PK4(p1, 8, pa3);
;     ...
; }
; template <int MODE>
; __device__ __forceinline__ void qkt(f32x16& p0, f32x16& p1, const bf16* Ks, const bf16x8* qr, int r32, int hi, float dq, float nsl, int side, float mi) {
;   if (MODE == 0) {
;     if (side != 0) {
;       const float sg = side > 0 ? -nsl : nsl, bb = -sg * dq - mi;
; #pragma unroll
;       for (int r = 0; r < 16; ++r) { const float c = (float)((r & 3) + 8 * (r >> 2)); p0[r] = fmaf(c, sg, bb); p1[r] = fmaf(c + 32.f, sg, bb); }
;     } else {
; #pragma unroll
;       for (int r = 0; r < 16; ++r) { const float c = (float)((r & 3) + 8 * (r >> 2)); p0[r] = fmaf(fabsf(dq - c), nsl, -mi); p1[r] = fmaf(fabsf(dq - (c + 32.f)), nsl, -mi); }
;     }
;   } else {
; #pragma unroll
;     for (int r = 0; r < 16; ++r) { const float c = (float)((r & 3) + 8 * (r >> 2)); p0[r] = (r < 8) ? fmaf(fabsf(dq - c), nsl, -mi) : NEGBIG; p1[r] = NEGBIG; }
;   }
; #pragma unroll
;   for (int d0 = 0; d0 < 8; ++d0) {
;     const int ko = r32 * 256 + ((((d0 & 3) * 32 + hi * 16) ^ ((r32 & 7) << 4))) + (d0 >> 2) * 128;
;     bf16x8 b0 = *reinterpret_cast<const bf16x8*>((const char*)Ks + ko);
;     bf16x8 b1 = *reinterpret_cast<const bf16x8*>((const char*)Ks + ko + 8192);
;     p0 = __builtin_amdgcn_mfma_f32_32x32x16_bf16(b0, qr[d0], p0, 0, 0, 0);
;     p1 = __builtin_amdgcn_mfma_f32_32x32x16_bf16(b1, qr[d0], p1, 0, 0, 0); }
; template <int J> ...
;     ...
;   SBAR(); qkt<0>(pB0, pB1, (bf16*)((char*)K_lds + SHM_K), qr, r32, hi, TILE_DQ(NT - 1), nsl, TILE_SIDE(NT - 1), mi);
;   finishSM(pA0, pA1, l_reg, pa0, pa1, pa2, pa3); SBAR();
;   pv_d0(o, vb0, pa0, pa1, pa2, pa3); SBAR();
.LBB0_708:
	s_movk_i32 s4, 0x70
	v_bitop3_b32 v0, v170, v222, s4 bitop3:0x78
	v_add3_u32 v173, 0, v0, v228
	ds_read_b128 v[0:3], v173 offset:49152
	ds_read_b128 v[4:7], v173 offset:57344
	s_movk_i32 s4, 0x60
	v_exp_f32_e32 v81, v81
	v_exp_f32_e32 v82, v82
	s_waitcnt lgkmcnt(1)
	v_mfma_f32_32x32x16_bf16 v[122:137], v[0:3], v[166:169], v[122:137]
	v_bitop3_b32 v0, v170, v221, 32 bitop3:0x36
	v_exp_f32_e32 v83, v83
	v_exp_f32_e32 v84, v84
	v_exp_f32_e32 v85, v85
	v_exp_f32_e32 v86, v86
	v_exp_f32_e32 v87, v87
	v_exp_f32_e32 v88, v88
	s_waitcnt lgkmcnt(0)
	v_mfma_f32_32x32x16_bf16 v[106:121], v[4:7], v[166:169], v[106:121]
	v_add3_u32 v166, 0, v0, v228
	ds_read_b128 v[0:3], v166 offset:49152
	ds_read_b128 v[4:7], v166 offset:57344
	v_exp_f32_e32 v89, v89
	s_and_b32 s3, s12, 0x3fffffc0
	s_lshl_b32 s3, s3, 2
	s_add_i32 s3, s3, 0
	s_add_i32 s3, s3, 0x10000
	s_waitcnt lgkmcnt(1)
	v_mfma_f32_32x32x16_bf16 v[122:137], v[0:3], v[162:165], v[122:137]
	v_bitop3_b32 v0, v170, v221, 64 bitop3:0x36
	s_waitcnt lgkmcnt(0)
	v_mfma_f32_32x32x16_bf16 v[106:121], v[4:7], v[162:165], v[106:121]
	v_add3_u32 v162, 0, v0, v228
	ds_read_b128 v[0:3], v162 offset:49152
	ds_read_b128 v[4:7], v162 offset:57344
	s_waitcnt lgkmcnt(1)
	v_mfma_f32_32x32x16_bf16 v[122:137], v[0:3], v[158:161], v[122:137]
	v_bitop3_b32 v0, v170, v221, s4 bitop3:0x36
	s_waitcnt lgkmcnt(0)
	v_mfma_f32_32x32x16_bf16 v[106:121], v[4:7], v[158:161], v[106:121]
	v_add3_u32 v158, 0, v0, v228
	ds_read_b128 v[0:3], v158 offset:49152
	ds_read_b128 v[4:7], v158 offset:57344
	s_waitcnt lgkmcnt(1)
	v_mfma_f32_32x32x16_bf16 v[122:137], v[0:3], v[154:157], v[122:137]
	s_waitcnt lgkmcnt(0)
	v_mfma_f32_32x32x16_bf16 v[106:121], v[4:7], v[154:157], v[106:121]
	ds_read_b128 v[0:3], v173 offset:49280
	ds_read_b128 v[4:7], v173 offset:57472
	s_waitcnt lgkmcnt(1)
	v_mfma_f32_32x32x16_bf16 v[122:137], v[0:3], v[150:153], v[122:137]
	s_waitcnt lgkmcnt(0)
	v_mfma_f32_32x32x16_bf16 v[106:121], v[4:7], v[150:153], v[106:121]
	ds_read_b128 v[0:3], v166 offset:49280
	ds_read_b128 v[4:7], v166 offset:57472
	s_waitcnt lgkmcnt(1)
	v_mfma_f32_32x32x16_bf16 v[122:137], v[0:3], v[146:149], v[122:137]
	s_waitcnt lgkmcnt(0)
	v_mfma_f32_32x32x16_bf16 v[106:121], v[4:7], v[146:149], v[106:121]
	ds_read_b128 v[0:3], v162 offset:49280
	ds_read_b128 v[4:7], v162 offset:57472
	s_waitcnt lgkmcnt(1)
	v_mfma_f32_32x32x16_bf16 v[122:137], v[0:3], v[142:145], v[122:137]
	s_waitcnt lgkmcnt(0)
	v_mfma_f32_32x32x16_bf16 v[106:121], v[4:7], v[142:145], v[106:121]
	ds_read_b128 v[0:3], v158 offset:49280
	ds_read_b128 v[4:7], v158 offset:57472
	s_waitcnt lgkmcnt(1)
	v_mfma_f32_32x32x16_bf16 v[122:137], v[0:3], v[138:141], v[122:137]
	v_exp_f32_e32 v1, v90
	v_exp_f32_e32 v3, v91
	v_exp_f32_e32 v90, v95
	v_exp_f32_e32 v91, v96
	v_add_f32_e32 v0, 0, v1
	v_add_f32_e32 v0, v3, v0
	v_exp_f32_e32 v95, v100
	s_waitcnt lgkmcnt(0)
	v_mfma_f32_32x32x16_bf16 v[106:121], v[4:7], v[138:141], v[106:121]
	v_exp_f32_e32 v5, v92
	v_exp_f32_e32 v6, v93
	v_exp_f32_e32 v7, v94
	v_exp_f32_e32 v92, v97
	v_add_f32_e32 v0, v5, v0
	v_add_f32_e32 v0, v6, v0
	v_exp_f32_e32 v93, v98
	v_add_f32_e32 v0, v7, v0
	v_exp_f32_e32 v94, v99
	v_add_f32_e32 v0, v90, v0
	v_add_f32_e32 v0, v91, v0
	v_exp_f32_e32 v96, v101
	v_add_f32_e32 v0, v92, v0
	v_exp_f32_e32 v97, v102
	v_add_f32_e32 v0, v93, v0
	v_exp_f32_e32 v98, v103
	v_add_f32_e32 v0, v94, v0
	v_exp_f32_e32 v99, v104
	v_add_f32_e32 v0, v95, v0
	v_exp_f32_e32 v100, v105
	v_add_f32_e32 v0, v96, v0
	v_exp_f32_e32 v101, v74
	v_add_f32_e32 v0, v97, v0
	v_exp_f32_e32 v102, v75
	v_add_f32_e32 v0, v98, v0
	v_exp_f32_e32 v103, v76
	v_add_f32_e32 v0, v99, v0
	v_exp_f32_e32 v104, v77
	v_add_f32_e32 v0, v100, v0
	v_exp_f32_e32 v105, v78
	v_add_f32_e32 v0, v101, v0
	v_exp_f32_e32 v138, v79
	v_add_f32_e32 v0, v102, v0
	v_exp_f32_e32 v139, v80
	v_add_f32_e32 v0, v103, v0
	v_add_f32_e32 v0, v104, v0
	v_add_f32_e32 v0, v105, v0
	v_add_f32_e32 v0, v138, v0
	v_add_f32_e32 v0, v139, v0
	v_add_f32_e32 v0, v81, v0
	v_add_f32_e32 v0, v82, v0
	v_add_f32_e32 v0, v83, v0
	v_add_f32_e32 v0, v84, v0
	v_add_f32_e32 v0, v85, v0
	v_add_f32_e32 v0, v86, v0
	v_add_f32_e32 v0, v87, v0
	v_add_f32_e32 v0, v88, v0
	v_add_f32_e32 v0, v89, v0
	v_mov_b32_e32 v2, v0
	s_nop 1
	v_permlane32_swap_b32_e32 v0, v2
	v_cvt_pk_bf16_f32 v4, v1, v3
	v_cvt_pk_bf16_f32 v5, v5, v6
	v_cvt_pk_bf16_f32 v6, v7, v90
	v_cvt_pk_bf16_f32 v7, v91, v92
	v_cvt_pk_bf16_f32 v74, v93, v94
	v_cvt_pk_bf16_f32 v75, v95, v96
	v_cvt_pk_bf16_f32 v76, v97, v98
	v_cvt_pk_bf16_f32 v77, v99, v100
	v_cvt_pk_bf16_f32 v78, v101, v102
	v_cvt_pk_bf16_f32 v79, v103, v104
	v_cvt_pk_bf16_f32 v80, v105, v138
	v_cvt_pk_bf16_f32 v81, v139, v81
	v_cvt_pk_bf16_f32 v82, v82, v83
	v_cvt_pk_bf16_f32 v83, v84, v85
	v_cvt_pk_bf16_f32 v84, v86, v87
	v_cvt_pk_bf16_f32 v85, v88, v89
	s_nop 0
	v_permlane32_swap_b32_e32 v4, v6
	v_permlane32_swap_b32_e32 v5, v7
	v_permlane32_swap_b32_e32 v74, v76
	v_permlane32_swap_b32_e32 v75, v77
	v_permlane32_swap_b32_e32 v78, v80
	v_permlane32_swap_b32_e32 v79, v81
	v_permlane32_swap_b32_e32 v82, v84
	v_permlane32_swap_b32_e32 v83, v85
	s_waitcnt lgkmcnt(0)
	ds_read_b64_tr_b16 v[86:87], v220 offset:0
	ds_read_b64_tr_b16 v[88:89], v220 offset:0x800
	ds_read_b64_tr_b16 v[90:91], v220 offset:0x1000
	ds_read_b64_tr_b16 v[92:93], v220 offset:0x1800
	ds_read_b64_tr_b16 v[94:95], v220 offset:0x2000
	ds_read_b64_tr_b16 v[96:97], v220 offset:0x2800
	ds_read_b64_tr_b16 v[98:99], v220 offset:0x3000
	ds_read_b64_tr_b16 v[100:101], v220 offset:0x3800
	s_waitcnt lgkmcnt(4)
; #define SBAR() __builtin_amdgcn_sched_barrier(0)
; #define PV_WAIT4() do { asm volatile("s_waitcnt lgkmcnt(4)" ::: "memory"); SBAR(); } while (0)
; #define PV_WAIT0() do { asm volatile("s_waitcnt lgkmcnt(0)" ::: "memory"); SBAR(); } while (0)
; #define PV_MM(od, pX, pY, g) do { od = __builtin_amdgcn_mfma_f32_32x32x16_bf16(pX, PK(g.l0, g.h0), od, 0, 0, 0); od = __builtin_amdgcn_mfma_f32_32x32x16_bf16(pY, PK(g.l1, g.h1), od, 0, 0, 0); } while (0)
; __device__ __forceinline__ void pv_d0(f32x16* o, int vb, bf16x8 pa0, bf16x8 pa1, bf16x8 pa2, bf16x8 pa3) {
;   asm volatile("s_waitcnt lgkmcnt(0)" ::: "memory");
;   VG a0 = pv_reads<0, 0>(vb), b0 = pv_reads<0, 2>(vb);
;   PV_WAIT4(); PV_MM(o[0], pa0, pa1, a0); VG a1 = pv_reads<1, 0>(vb);
;   PV_WAIT4(); PV_MM(o[0], pa2, pa3, b0); VG b1 = pv_reads<1, 2>(vb);
;   PV_WAIT4(); PV_MM(o[1], pa0, pa1, a1); VG a2 = pv_reads<2, 0>(vb);
;   PV_WAIT4(); PV_MM(o[1], pa2, pa3, b1); VG b2 = pv_reads<2, 2>(vb);
;   PV_WAIT4(); PV_MM(o[2], pa0, pa1, a2); VG a3 = pv_reads<3, 0>(vb);
;   PV_WAIT4(); PV_MM(o[2], pa2, pa3, b2); VG b3 = pv_reads<3, 2>(vb);
;   PV_WAIT4(); PV_MM(o[3], pa0, pa1, a3);
;   PV_WAIT0(); PV_MM(o[3], pa2, pa3, b3);
; }
; template <int J> ...
;     ...
;   pv_d0(o, vb0, pa0, pa1, pa2, pa3); SBAR();
;   __syncthreads();
;   finishSM(pB0, pB1, l_reg, pa0, pa1, pa2, pa3); SBAR();
	s_nop 0
	v_mfma_f32_32x32x16_bf16 v[58:73], v[4:7], v[86:89], v[58:73]
	ds_read_b64_tr_b16 v[86:87], v220 offset:0x200
	ds_read_b64_tr_b16 v[88:89], v220 offset:0xa00
	v_mfma_f32_32x32x16_bf16 v[58:73], v[74:77], v[90:93], v[58:73]
	ds_read_b64_tr_b16 v[90:91], v220 offset:0x1200
	ds_read_b64_tr_b16 v[92:93], v220 offset:0x1a00
	s_waitcnt lgkmcnt(4)
	v_mfma_f32_32x32x16_bf16 v[58:73], v[78:81], v[94:97], v[58:73]
	ds_read_b64_tr_b16 v[94:95], v220 offset:0x2200
	ds_read_b64_tr_b16 v[96:97], v220 offset:0x2a00
	v_mfma_f32_32x32x16_bf16 v[58:73], v[82:85], v[98:101], v[58:73]
	ds_read_b64_tr_b16 v[98:99], v220 offset:0x3200
	ds_read_b64_tr_b16 v[100:101], v220 offset:0x3a00
	s_waitcnt lgkmcnt(4)
	v_mfma_f32_32x32x16_bf16 v[42:57], v[4:7], v[86:89], v[42:57]
	ds_read_b64_tr_b16 v[86:87], v220 offset:0x400
	ds_read_b64_tr_b16 v[88:89], v220 offset:0xc00
	v_mfma_f32_32x32x16_bf16 v[42:57], v[74:77], v[90:93], v[42:57]
	ds_read_b64_tr_b16 v[90:91], v220 offset:0x1400
	ds_read_b64_tr_b16 v[92:93], v220 offset:0x1c00
	s_waitcnt lgkmcnt(4)
	v_mfma_f32_32x32x16_bf16 v[42:57], v[78:81], v[94:97], v[42:57]
	ds_read_b64_tr_b16 v[94:95], v220 offset:0x2400
	ds_read_b64_tr_b16 v[96:97], v220 offset:0x2c00
	v_mfma_f32_32x32x16_bf16 v[42:57], v[82:85], v[98:101], v[42:57]
	ds_read_b64_tr_b16 v[98:99], v220 offset:0x3400
	ds_read_b64_tr_b16 v[100:101], v220 offset:0x3c00
	s_waitcnt lgkmcnt(4)
	v_mfma_f32_32x32x16_bf16 v[26:41], v[4:7], v[86:89], v[26:41]
	ds_read_b64_tr_b16 v[86:87], v220 offset:0x600
	ds_read_b64_tr_b16 v[88:89], v220 offset:0xe00
	v_mfma_f32_32x32x16_bf16 v[26:41], v[74:77], v[90:93], v[26:41]
	ds_read_b64_tr_b16 v[90:91], v220 offset:0x1600
	ds_read_b64_tr_b16 v[92:93], v220 offset:0x1e00
	s_waitcnt lgkmcnt(4)
	v_mfma_f32_32x32x16_bf16 v[26:41], v[78:81], v[94:97], v[26:41]
	ds_read_b64_tr_b16 v[94:95], v220 offset:0x2600
	ds_read_b64_tr_b16 v[96:97], v220 offset:0x2e00
	v_mfma_f32_32x32x16_bf16 v[26:41], v[82:85], v[98:101], v[26:41]
	ds_read_b64_tr_b16 v[98:99], v220 offset:0x3600
	ds_read_b64_tr_b16 v[100:101], v220 offset:0x3e00
	s_waitcnt lgkmcnt(4)
	v_mfma_f32_32x32x16_bf16 v[10:25], v[4:7], v[86:89], v[10:25]
	s_waitcnt lgkmcnt(0)
	v_mfma_f32_32x32x16_bf16 v[10:25], v[74:77], v[90:93], v[10:25]
	v_mfma_f32_32x32x16_bf16 v[10:25], v[78:81], v[94:97], v[10:25]
	v_mfma_f32_32x32x16_bf16 v[10:25], v[82:85], v[98:101], v[10:25]
	v_exp_f32_e32 v4, v122
	v_exp_f32_e32 v5, v123
	v_exp_f32_e32 v6, v124
	v_exp_f32_e32 v7, v125
	v_exp_f32_e32 v74, v126
	v_add_f32_e32 v1, 0, v4
	v_exp_f32_e32 v75, v127
	v_add_f32_e32 v1, v5, v1
	v_exp_f32_e32 v76, v128
	v_add_f32_e32 v1, v6, v1
	v_exp_f32_e32 v77, v129
	v_add_f32_e32 v1, v7, v1
	v_exp_f32_e32 v78, v130
	v_add_f32_e32 v1, v74, v1
	v_exp_f32_e32 v79, v131
	v_add_f32_e32 v1, v75, v1
	v_exp_f32_e32 v80, v132
	v_add_f32_e32 v1, v76, v1
	v_exp_f32_e32 v81, v133
	v_add_f32_e32 v1, v77, v1
	v_exp_f32_e32 v82, v134
	v_add_f32_e32 v1, v78, v1
	v_exp_f32_e32 v83, v135
	v_add_f32_e32 v1, v79, v1
	v_exp_f32_e32 v84, v136
	v_add_f32_e32 v1, v80, v1
	v_exp_f32_e32 v85, v137
	v_add_f32_e32 v1, v81, v1
	v_exp_f32_e32 v86, v106
	v_add_f32_e32 v1, v82, v1
	v_exp_f32_e32 v87, v107
	v_add_f32_e32 v1, v83, v1
	v_exp_f32_e32 v88, v108
	v_add_f32_e32 v1, v84, v1
	v_exp_f32_e32 v89, v109
	v_add_f32_e32 v1, v85, v1
	v_exp_f32_e32 v90, v110
	v_add_f32_e32 v1, v86, v1
	v_exp_f32_e32 v91, v111
	v_add_f32_e32 v1, v87, v1
	v_exp_f32_e32 v92, v112
	v_add_f32_e32 v1, v88, v1
	v_exp_f32_e32 v93, v113
	v_add_f32_e32 v1, v89, v1
	v_exp_f32_e32 v94, v114
	v_add_f32_e32 v1, v90, v1
	v_exp_f32_e32 v95, v115
	v_add_f32_e32 v1, v91, v1
	v_exp_f32_e32 v96, v116
	v_add_f32_e32 v1, v92, v1
	v_exp_f32_e32 v97, v117
	v_add_f32_e32 v1, v93, v1
	v_exp_f32_e32 v98, v118
	v_add_f32_e32 v1, v94, v1
	v_exp_f32_e32 v99, v119
	v_add_f32_e32 v1, v95, v1
	v_exp_f32_e32 v100, v120
	v_add_f32_e32 v1, v96, v1
	v_exp_f32_e32 v101, v121
	v_add_f32_e32 v1, v97, v1
	v_add_f32_e32 v1, v98, v1
	v_add_f32_e32 v1, v99, v1
	v_add_f32_e32 v1, v100, v1
	v_add_f32_e32 v1, v101, v1
	v_mov_b32_e32 v3, v1
	s_waitcnt vmcnt(0)
	s_barrier
; #define ATT_GAS __attribute__((address_space(1)))
; __device__ __forceinline__ int crow(int r, int hi) { return (r & 3) + 8 * (r >> 2) + 4 * hi; }
; __device__ __forceinline__ float bf2f(bf16 v) { return __uint_as_float((unsigned)v << 16); }
; __device__ __forceinline__ bf16 f2bf(float f) { unsigned u = __float_as_uint(f); return (bf16)((u + 0x7fffu + ((u >> 16) & 1u)) >> 16); }
; template <int J> ...
;     ...
;   pv_d0(o, vb0 + (int)SHM_V, pa0, pa1, pa2, pa3);
;   if (hi == 0) li_l[r32] = l_reg; asm volatile("s_waitcnt lgkmcnt(0)" ::: "memory");
;   float rli[16];
; #pragma unroll
;   for (int r = 0; r < 16; ++r) rli[r] = __builtin_amdgcn_rcpf(li_l[crow(r, hi)]);
;   bf16* Ow = Ob + (long)(wid * QBLK) * LD; const float lam = (J == 0) ? *(const float*)(lds + SHM_ATTN + 4) : 0.f;
; #pragma unroll
;   for (int r = 0; r < 16; ++r) { const int orow = crow(r, hi);
;     if (wid * QBLK + orow < nvalid) {
; #pragma unroll
;       for (int d0 = 0; d0 < 4; ++d0) { ATT_GAS bf16* p = (ATT_GAS bf16*)(Ow + (long)orow * LD + d0 * 32 + r32); const float v = o[d0][r] * rli[r];
;         if (J == 1) *p = f2bf(v); else *p = f2bf(v - lam * bf2f(*p)); } } }
	s_nop 0
	v_permlane32_swap_b32_e32 v1, v3
	v_cvt_pk_bf16_f32 v4, v4, v5
	v_cvt_pk_bf16_f32 v5, v6, v7
	v_cvt_pk_bf16_f32 v6, v74, v75
	v_cvt_pk_bf16_f32 v7, v76, v77
	v_cvt_pk_bf16_f32 v74, v78, v79
	v_cvt_pk_bf16_f32 v75, v80, v81
	v_cvt_pk_bf16_f32 v76, v82, v83
	v_cvt_pk_bf16_f32 v77, v84, v85
	v_cvt_pk_bf16_f32 v78, v86, v87
	v_cvt_pk_bf16_f32 v79, v88, v89
	v_cvt_pk_bf16_f32 v80, v90, v91
	v_cvt_pk_bf16_f32 v81, v92, v93
	v_cvt_pk_bf16_f32 v82, v94, v95
	v_cvt_pk_bf16_f32 v83, v96, v97
	v_cvt_pk_bf16_f32 v84, v98, v99
	v_cvt_pk_bf16_f32 v85, v100, v101
	s_nop 0
	v_permlane32_swap_b32_e32 v4, v6
	v_permlane32_swap_b32_e32 v5, v7
	v_permlane32_swap_b32_e32 v74, v76
	v_permlane32_swap_b32_e32 v75, v77
	v_permlane32_swap_b32_e32 v78, v80
	v_permlane32_swap_b32_e32 v79, v81
	v_permlane32_swap_b32_e32 v82, v84
	v_permlane32_swap_b32_e32 v83, v85
	s_cmp_lg_u32 0, -1
	s_cselect_b32 s4, 0, 0
	s_addk_i32 s4, 0x4000
	s_waitcnt lgkmcnt(0)
	v_add_u32_e32 v102, s4, v219
	ds_read_b64_tr_b16 v[86:87], v102 offset:0
	ds_read_b64_tr_b16 v[88:89], v102 offset:0x800
	ds_read_b64_tr_b16 v[90:91], v102 offset:0x1000
	ds_read_b64_tr_b16 v[92:93], v102 offset:0x1800
	ds_read_b64_tr_b16 v[94:95], v102 offset:0x2000
	ds_read_b64_tr_b16 v[96:97], v102 offset:0x2800
	ds_read_b64_tr_b16 v[98:99], v102 offset:0x3000
	ds_read_b64_tr_b16 v[100:101], v102 offset:0x3800
	s_waitcnt lgkmcnt(4)
	s_nop 0
	v_mfma_f32_32x32x16_bf16 v[58:73], v[4:7], v[86:89], v[58:73]
	ds_read_b64_tr_b16 v[86:87], v102 offset:0x200
	ds_read_b64_tr_b16 v[88:89], v102 offset:0xa00
	v_mfma_f32_32x32x16_bf16 v[58:73], v[74:77], v[90:93], v[58:73]
	ds_read_b64_tr_b16 v[90:91], v102 offset:0x1200
	ds_read_b64_tr_b16 v[92:93], v102 offset:0x1a00
	s_waitcnt lgkmcnt(4)
	v_mfma_f32_32x32x16_bf16 v[58:73], v[78:81], v[94:97], v[58:73]
	ds_read_b64_tr_b16 v[94:95], v102 offset:0x2200
	ds_read_b64_tr_b16 v[96:97], v102 offset:0x2a00
	v_mfma_f32_32x32x16_bf16 v[58:73], v[82:85], v[98:101], v[58:73]
	ds_read_b64_tr_b16 v[98:99], v102 offset:0x3200
	ds_read_b64_tr_b16 v[100:101], v102 offset:0x3a00
	s_waitcnt lgkmcnt(4)
	v_mfma_f32_32x32x16_bf16 v[42:57], v[4:7], v[86:89], v[42:57]
	ds_read_b64_tr_b16 v[86:87], v102 offset:0x400
	ds_read_b64_tr_b16 v[88:89], v102 offset:0xc00
	v_mfma_f32_32x32x16_bf16 v[42:57], v[74:77], v[90:93], v[42:57]
	ds_read_b64_tr_b16 v[90:91], v102 offset:0x1400
	ds_read_b64_tr_b16 v[92:93], v102 offset:0x1c00
	s_waitcnt lgkmcnt(4)
	v_mfma_f32_32x32x16_bf16 v[42:57], v[78:81], v[94:97], v[42:57]
	ds_read_b64_tr_b16 v[94:95], v102 offset:0x2400
	ds_read_b64_tr_b16 v[96:97], v102 offset:0x2c00
	v_mfma_f32_32x32x16_bf16 v[42:57], v[82:85], v[98:101], v[42:57]
	ds_read_b64_tr_b16 v[98:99], v102 offset:0x3400
	ds_read_b64_tr_b16 v[100:101], v102 offset:0x3c00
	s_waitcnt lgkmcnt(4)
	v_mfma_f32_32x32x16_bf16 v[26:41], v[4:7], v[86:89], v[26:41]
	ds_read_b64_tr_b16 v[86:87], v102 offset:0x600
	ds_read_b64_tr_b16 v[88:89], v102 offset:0xe00
	v_mfma_f32_32x32x16_bf16 v[26:41], v[74:77], v[90:93], v[26:41]
	ds_read_b64_tr_b16 v[90:91], v102 offset:0x1600
	ds_read_b64_tr_b16 v[92:93], v102 offset:0x1e00
	s_waitcnt lgkmcnt(4)
	v_mfma_f32_32x32x16_bf16 v[26:41], v[78:81], v[94:97], v[26:41]
	ds_read_b64_tr_b16 v[94:95], v102 offset:0x2600
	ds_read_b64_tr_b16 v[96:97], v102 offset:0x2e00
	v_mfma_f32_32x32x16_bf16 v[26:41], v[82:85], v[98:101], v[26:41]
	ds_read_b64_tr_b16 v[98:99], v102 offset:0x3600
	ds_read_b64_tr_b16 v[100:101], v102 offset:0x3e00
	s_waitcnt lgkmcnt(4)
	v_mfma_f32_32x32x16_bf16 v[10:25], v[4:7], v[86:89], v[10:25]
	s_waitcnt lgkmcnt(0)
	v_mfma_f32_32x32x16_bf16 v[10:25], v[74:77], v[90:93], v[10:25]
	v_mfma_f32_32x32x16_bf16 v[10:25], v[78:81], v[94:97], v[10:25]
	v_cmp_gt_u32_e32 vcc, 32, v9
	v_mfma_f32_32x32x16_bf16 v[10:25], v[82:85], v[98:101], v[10:25]
	s_and_saveexec_b64 s[4:5], vcc
	v_pk_add_f32 v[0:1], v[0:1], v[2:3]
	v_lshl_add_u32 v4, v218, 2, s3
	v_add_f32_e32 v0, v227, v0
	v_add_f32_e32 v0, v0, v1
	ds_write_b32 v4, v0
	s_or_b64 exec, exec, s[4:5]
	s_ashr_i32 s23, s22, 31
	v_lshl_add_u32 v78, v216, 2, s3
	s_lshl_b64 s[4:5], s[22:23], 12
	v_readlane_b32 s3, v244, 7
	s_waitcnt lgkmcnt(0)
	s_add_u32 s4, s3, s4
	v_readlane_b32 s3, v244, 10
	ds_read2_b32 v[82:83], v78 offset0:1 offset1:2
	ds_read_b32 v9, v78 offset:12
	ds_read_b128 v[74:77], v78 offset:32
	ds_read_b128 v[4:7], v78 offset:64
	s_addc_u32 s5, s3, s5
	v_readlane_b32 s3, v244, 32
	v_lshlrev_b32_e32 v170, 1, v218
	v_or_b32_e32 v84, s22, v216
	v_mov_b32_e32 v79, s3
	ds_read_b128 v[0:3], v78 offset:96
	ds_read_b32 v79, v79
	v_lshl_add_u64 v[80:81], s[4:5], 0, v[170:171]
	v_cmp_gt_i32_e32 vcc, s8, v84
	s_and_saveexec_b64 s[4:5], vcc
	s_cbranch_execz .LBB0_712
	v_lshlrev_b32_e32 v170, 14, v217
	v_lshl_add_u64 v[84:85], v[80:81], 0, v[170:171]
	global_load_ushort v86, v[84:85], off
	ds_read_b32 v78, v78
	s_waitcnt lgkmcnt(0)
	v_rcp_f32_e32 v78, v78
	s_waitcnt vmcnt(0)
	v_lshlrev_b32_e32 v86, 16, v86
	v_mul_f32_e32 v86, v79, v86
	v_fma_f32 v58, v58, v78, -v86
	v_bfe_u32 v86, v58, 16, 1
	v_add3_u32 v58, v58, v86, s26
	global_store_short_d16_hi v[84:85], v58, off
	global_load_ushort v58, v[84:85], off offset:64
	s_waitcnt vmcnt(0)
	v_lshlrev_b32_e32 v58, 16, v58
	v_mul_f32_e32 v58, v79, v58
	v_fma_f32 v42, v42, v78, -v58
	v_bfe_u32 v58, v42, 16, 1
	v_add3_u32 v42, v42, v58, s26
	global_store_short_d16_hi v[84:85], v42, off offset:64
	global_load_ushort v42, v[84:85], off offset:128
	s_waitcnt vmcnt(0)
	v_lshlrev_b32_e32 v42, 16, v42
	v_mul_f32_e32 v42, v79, v42
	v_fma_f32 v26, v26, v78, -v42
	v_bfe_u32 v42, v26, 16, 1
	v_add3_u32 v26, v26, v42, s26
	global_store_short_d16_hi v[84:85], v26, off offset:128
	global_load_ushort v26, v[84:85], off offset:192
	s_waitcnt vmcnt(0)
	v_lshlrev_b32_e32 v26, 16, v26
	v_mul_f32_e32 v26, v79, v26
	v_fma_f32 v10, v10, v78, -v26
	v_bfe_u32 v26, v10, 16, 1
	v_add3_u32 v10, v10, v26, s26
	global_store_short_d16_hi v[84:85], v10, off offset:192

; __device__ __forceinline__ void finishSM(f32x16& p0, f32x16& p1, float& l_reg, bf16x8& pa0, bf16x8& pa1, bf16x8& pa2, bf16x8& pa3) {
; #pragma unroll
;   for (int r = 0; r < 16; ++r) p0[r] = __builtin_amdgcn_exp2f(p0[r]);
; #pragma unroll
;   for (int r = 0; r < 16; ++r) p1[r] = __builtin_amdgcn_exp2f(p1[r]);
;   float ps = 0;
; #pragma unroll
;   for (int r = 0; r < 16; ++r) ps += p0[r];
; #pragma unroll
;   for (int r = 0; r < 16; ++r) ps += p1[r];
;   { auto rr = __builtin_amdgcn_permlane32_swap(__float_as_uint(ps), __float_as_uint(ps), false, false);
;     ps = __uint_as_float(rr[0]) + __uint_as_float(rr[1]); }
;   l_reg += ps;
;     ...
;   PK4(p0, 0, pa0); PK4(p0, 8, pa1); PK4(p1, 0, pa2); PK4(p1, 8, pa3);
;     ...
; }
; template <int MODE>
; __device__ __forceinline__ void qkt(f32x16& p0, f32x16& p1, const bf16* Ks, const bf16x8* qr, int r32, int hi, float dq, float nsl, int side, float mi) {
;   if (MODE == 0) {
;     if (side != 0) {
;       const float sg = side > 0 ? -nsl : nsl, bb = -sg * dq - mi;
; #pragma unroll
;       for (int r = 0; r < 16; ++r) { const float c = (float)((r & 3) + 8 * (r >> 2)); p0[r] = fmaf(c, sg, bb); p1[r] = fmaf(c + 32.f, sg, bb); }
;     } else {
; #pragma unroll
;       for (int r = 0; r < 16; ++r) { const float c = (float)((r & 3) + 8 * (r >> 2)); p0[r] = fmaf(fabsf(dq - c), nsl, -mi); p1[r] = fmaf(fabsf(dq - (c + 32.f)), nsl, -mi); }
;     }
;   } else {
; #pragma unroll
;     for (int r = 0; r < 16; ++r) { const float c = (float)((r & 3) + 8 * (r >> 2)); p0[r] = (r < 8) ? fmaf(fabsf(dq - c), nsl, -mi) : NEGBIG; p1[r] = NEGBIG; }
;   }
; #pragma unroll
;   for (int d0 = 0; d0 < 8; ++d0) {
;     const int ko = r32 * 256 + ((((d0 & 3) * 32 + hi * 16) ^ ((r32 & 7) << 4))) + (d0 >> 2) * 128;
;     bf16x8 b0 = *reinterpret_cast<const bf16x8*>((const char*)Ks + ko);
;     bf16x8 b1 = *reinterpret_cast<const bf16x8*>((const char*)Ks + ko + 8192);
;     p0 = __builtin_amdgcn_mfma_f32_32x32x16_bf16(b0, qr[d0], p0, 0, 0, 0);
;     p1 = __builtin_amdgcn_mfma_f32_32x32x16_bf16(b1, qr[d0], p1, 0, 0, 0); }
; template <int J> ...
;     ...
;     SBAR(); qkt<0>(pB0, pB1, (bf16*)((char*)K_lds + SHM_K), qr, r32, hi, TILE_DQ(j), nsl, TILE_SIDE(j), mi);
;     finishSM(pA0, pA1, l_reg, pa0, pa1, pa2, pa3); SBAR();
;     SLOAD(SO, j + SDEPTH); SBAR();
;     pv_d0(o, vb0, pa0, pa1, pa2, pa3); SBAR();
;     __syncthreads(); SWAIT(); SWRITE(0, SE);
.LBB0_757:
	v_readfirstlane_b32 s92, v248
	s_add_i32 s4, s20, s30
	s_add_i32 s10, s4, 1
	s_ashr_i32 s11, s10, 31
	s_lshl_b64 s[10:11], s[10:11], 18
	s_add_u32 s10, s89, s10
	s_addc_u32 s11, s24, s11
	s_add_i32 s5, s30, 1
	s_cmp_lt_i32 s5, s15
	s_cselect_b32 s10, s10, s16
	s_cselect_b32 s11, s11, s1
	s_ashr_i32 s5, s4, 31
	s_lshl_b64 s[4:5], s[4:5], 18
	s_add_u32 s4, s0, s4
	s_addc_u32 s5, s25, s5
	s_add_i32 m0, s92, 0x8000
	s_nop 0
	global_load_lds_dwordx4 v245, s[10:11]
	s_add_i32 m0, s92, 0x8400
	s_nop 0
	global_load_lds_dwordx4 v246, s[10:11]
	s_add_i32 m0, s92, 0x4000
	s_nop 0
	global_load_lds_dwordx4 v247, s[4:5]
	s_add_i32 m0, s92, 0x4380
	s_nop 0
	global_load_lds_dwordx4 v247, s[4:5] offset:128
	ds_read_b128 v[0:3], v229 offset:49152
	ds_read_b128 v[4:7], v229 offset:57344
	v_exp_f32_e32 v74, v74
	v_exp_f32_e32 v75, v75
	v_exp_f32_e32 v76, v76
	s_waitcnt lgkmcnt(1)
	v_mfma_f32_32x32x16_bf16 v[122:137], v[0:3], v[158:161], v[122:137]
	v_exp_f32_e32 v77, v77
	v_exp_f32_e32 v78, v78
	v_exp_f32_e32 v79, v79
	v_exp_f32_e32 v80, v80
	v_exp_f32_e32 v81, v81
	v_exp_f32_e32 v82, v82
	v_exp_f32_e32 v83, v83
	s_waitcnt lgkmcnt(0)
	v_mfma_f32_32x32x16_bf16 v[106:121], v[4:7], v[158:161], v[106:121]
	ds_read_b128 v[0:3], v230 offset:49152
	ds_read_b128 v[4:7], v230 offset:57344
	v_exp_f32_e32 v84, v84
	v_exp_f32_e32 v85, v85
	v_exp_f32_e32 v86, v86
	v_exp_f32_e32 v87, v87
	v_exp_f32_e32 v88, v88
	v_exp_f32_e32 v89, v89
	s_waitcnt lgkmcnt(1)
	v_mfma_f32_32x32x16_bf16 v[122:137], v[0:3], v[154:157], v[122:137]
	s_add_i32 s4, s30, 1
	s_waitcnt lgkmcnt(0)
	v_mfma_f32_32x32x16_bf16 v[106:121], v[4:7], v[154:157], v[106:121]
	ds_read_b128 v[0:3], v231 offset:49152
	ds_read_b128 v[4:7], v231 offset:57344
	s_waitcnt lgkmcnt(1)
	v_mfma_f32_32x32x16_bf16 v[122:137], v[0:3], v[150:153], v[122:137]
	s_waitcnt lgkmcnt(0)
	v_mfma_f32_32x32x16_bf16 v[106:121], v[4:7], v[150:153], v[106:121]
	ds_read_b128 v[0:3], v232 offset:49152
	ds_read_b128 v[4:7], v232 offset:57344
	s_waitcnt lgkmcnt(1)
	v_mfma_f32_32x32x16_bf16 v[122:137], v[0:3], v[146:149], v[122:137]
	s_waitcnt lgkmcnt(0)
	v_mfma_f32_32x32x16_bf16 v[106:121], v[4:7], v[146:149], v[106:121]
	ds_read_b128 v[0:3], v229 offset:49280
	ds_read_b128 v[4:7], v229 offset:57472
	s_waitcnt lgkmcnt(1)
	v_mfma_f32_32x32x16_bf16 v[122:137], v[0:3], v[142:145], v[122:137]
	s_waitcnt lgkmcnt(0)
	v_mfma_f32_32x32x16_bf16 v[106:121], v[4:7], v[142:145], v[106:121]
	ds_read_b128 v[0:3], v230 offset:49280
	ds_read_b128 v[4:7], v230 offset:57472
	s_waitcnt lgkmcnt(1)
	v_mfma_f32_32x32x16_bf16 v[122:137], v[0:3], v[138:141], v[122:137]
	s_waitcnt lgkmcnt(0)
	v_mfma_f32_32x32x16_bf16 v[106:121], v[4:7], v[138:141], v[106:121]
	ds_read_b128 v[0:3], v231 offset:49280
	ds_read_b128 v[4:7], v231 offset:57472
	s_waitcnt lgkmcnt(1)
	v_mfma_f32_32x32x16_bf16 v[122:137], v[0:3], v[166:169], v[122:137]
	s_waitcnt lgkmcnt(0)
	v_mfma_f32_32x32x16_bf16 v[106:121], v[4:7], v[166:169], v[106:121]
	ds_read_b128 v[0:3], v232 offset:49280
	ds_read_b128 v[4:7], v232 offset:57472
	s_waitcnt lgkmcnt(1)
	v_mfma_f32_32x32x16_bf16 v[122:137], v[0:3], v[162:165], v[122:137]
	v_exp_f32_e32 v0, v90
	v_exp_f32_e32 v1, v91
	v_exp_f32_e32 v2, v92
	v_exp_f32_e32 v3, v93
	v_exp_f32_e32 v90, v98
	v_add_f32_e32 v98, 0, v0
	v_add_f32_e32 v98, v1, v98
	s_waitcnt lgkmcnt(0)
	v_mfma_f32_32x32x16_bf16 v[106:121], v[4:7], v[162:165], v[106:121]
	v_exp_f32_e32 v4, v94
	v_exp_f32_e32 v5, v95
	v_exp_f32_e32 v6, v96
	v_add_f32_e32 v98, v2, v98
	v_exp_f32_e32 v7, v97
	v_add_f32_e32 v98, v3, v98
	v_add_f32_e32 v98, v4, v98
	v_exp_f32_e32 v91, v99
	v_add_f32_e32 v98, v5, v98
	v_exp_f32_e32 v92, v100
	v_add_f32_e32 v98, v6, v98
	v_exp_f32_e32 v93, v101
	v_add_f32_e32 v98, v7, v98
	v_exp_f32_e32 v94, v102
	v_add_f32_e32 v98, v90, v98
	v_exp_f32_e32 v95, v103
	v_add_f32_e32 v98, v91, v98
	v_exp_f32_e32 v96, v104
	v_add_f32_e32 v98, v92, v98
	v_exp_f32_e32 v97, v105
	v_add_f32_e32 v98, v93, v98
	v_add_f32_e32 v98, v94, v98
	v_add_f32_e32 v98, v95, v98
	v_add_f32_e32 v98, v96, v98
	v_add_f32_e32 v98, v97, v98
	v_add_f32_e32 v98, v74, v98
	v_add_f32_e32 v98, v75, v98
	v_add_f32_e32 v98, v76, v98
	v_add_f32_e32 v98, v77, v98
	v_add_f32_e32 v98, v78, v98
	v_add_f32_e32 v98, v79, v98
	v_add_f32_e32 v98, v80, v98
	v_add_f32_e32 v98, v81, v98
	v_add_f32_e32 v98, v82, v98
	v_add_f32_e32 v98, v83, v98
	v_add_f32_e32 v98, v84, v98
	v_add_f32_e32 v98, v85, v98
	v_add_f32_e32 v98, v86, v98
	v_add_f32_e32 v98, v87, v98
	v_add_f32_e32 v98, v88, v98
	v_add_f32_e32 v233, v89, v98
	v_mov_b32_e32 v234, v233
	v_cvt_pk_bf16_f32 v0, v0, v1
	v_cvt_pk_bf16_f32 v1, v2, v3
	v_cvt_pk_bf16_f32 v2, v4, v5
	v_cvt_pk_bf16_f32 v3, v6, v7
	v_cvt_pk_bf16_f32 v4, v90, v91
	v_cvt_pk_bf16_f32 v5, v92, v93
	v_cvt_pk_bf16_f32 v6, v94, v95
	v_cvt_pk_bf16_f32 v7, v96, v97
	v_cvt_pk_bf16_f32 v74, v74, v75
	v_cvt_pk_bf16_f32 v75, v76, v77
	v_cvt_pk_bf16_f32 v76, v78, v79
	v_cvt_pk_bf16_f32 v77, v80, v81
	v_cvt_pk_bf16_f32 v78, v82, v83
	v_cvt_pk_bf16_f32 v79, v84, v85
	v_cvt_pk_bf16_f32 v80, v86, v87
	v_cvt_pk_bf16_f32 v81, v88, v89
	s_nop 1
	v_permlane32_swap_b32_e32 v233, v234
	v_permlane32_swap_b32_e32 v0, v2
	v_permlane32_swap_b32_e32 v74, v76
	v_permlane32_swap_b32_e32 v75, v77
	v_permlane32_swap_b32_e32 v78, v80
	v_permlane32_swap_b32_e32 v79, v81
	v_permlane32_swap_b32_e32 v1, v3
	v_permlane32_swap_b32_e32 v4, v6
	v_permlane32_swap_b32_e32 v5, v7
	s_add_i32 s3, s20, s30
	s_add_i32 s10, s3, 1
	s_ashr_i32 s11, s10, 31
	s_lshl_b64 s[10:11], s[10:11], 18
	s_add_u32 s9, s89, s10
	s_addc_u32 s31, s24, s11
	s_add_u32 s10, s0, s10
	s_addc_u32 s11, s25, s11
	s_cmp_lt_i32 s4, s15
	s_cselect_b64 vcc, -1, 0
	s_and_b64 s[4:5], vcc, exec
	s_cselect_b32 s5, s31, s1
	s_cselect_b32 s4, s9, s16
	s_cselect_b32 s11, s11, s29
	s_cselect_b32 s10, s10, s28
	s_waitcnt lgkmcnt(0)
; #define PV_WAIT4() do { asm volatile("s_waitcnt lgkmcnt(4)" ::: "memory"); SBAR(); } while (0)
; #define PV_WAIT0() do { asm volatile("s_waitcnt lgkmcnt(0)" ::: "memory"); SBAR(); } while (0)
; #define PV_MM(od, pX, pY, g) do { od = __builtin_amdgcn_mfma_f32_32x32x16_bf16(pX, PK(g.l0, g.h0), od, 0, 0, 0); od = __builtin_amdgcn_mfma_f32_32x32x16_bf16(pY, PK(g.l1, g.h1), od, 0, 0, 0); } while (0)
; template <int MODE>
; __device__ __forceinline__ void qkt(f32x16& p0, f32x16& p1, const bf16* Ks, const bf16x8* qr, int r32, int hi, float dq, float nsl, int side, float mi) {
;   if (MODE == 0) {
;     if (side != 0) {
;       const float sg = side > 0 ? -nsl : nsl, bb = -sg * dq - mi;
; #pragma unroll
;       for (int r = 0; r < 16; ++r) { const float c = (float)((r & 3) + 8 * (r >> 2)); p0[r] = fmaf(c, sg, bb); p1[r] = fmaf(c + 32.f, sg, bb); }
;     } else {
; #pragma unroll
;       for (int r = 0; r < 16; ++r) { const float c = (float)((r & 3) + 8 * (r >> 2)); p0[r] = fmaf(fabsf(dq - c), nsl, -mi); p1[r] = fmaf(fabsf(dq - (c + 32.f)), nsl, -mi); }
;     }
; __device__ __forceinline__ void pv_d0(f32x16* o, int vb, bf16x8 pa0, bf16x8 pa1, bf16x8 pa2, bf16x8 pa3) {
;   asm volatile("s_waitcnt lgkmcnt(0)" ::: "memory");
;   VG a0 = pv_reads<0, 0>(vb), b0 = pv_reads<0, 2>(vb);
;   PV_WAIT4(); PV_MM(o[0], pa0, pa1, a0); VG a1 = pv_reads<1, 0>(vb);
;   PV_WAIT4(); PV_MM(o[0], pa2, pa3, b0); VG b1 = pv_reads<1, 2>(vb);
;   PV_WAIT4(); PV_MM(o[1], pa0, pa1, a1); VG a2 = pv_reads<2, 0>(vb);
;   PV_WAIT4(); PV_MM(o[1], pa2, pa3, b1); VG b2 = pv_reads<2, 2>(vb);
;   PV_WAIT4(); PV_MM(o[2], pa0, pa1, a2); VG a3 = pv_reads<3, 0>(vb);
;   PV_WAIT4(); PV_MM(o[2], pa2, pa3, b2); VG b3 = pv_reads<3, 2>(vb);
;   PV_WAIT4(); PV_MM(o[3], pa0, pa1, a3);
;   PV_WAIT0(); PV_MM(o[3], pa2, pa3, b3);
; }
	ds_read_b64_tr_b16 v[98:99], v219 offset:0
	ds_read_b64_tr_b16 v[100:101], v219 offset:0x800
	ds_read_b64_tr_b16 v[102:103], v219 offset:0x1000
	ds_read_b64_tr_b16 v[104:105], v219 offset:0x1800
	ds_read_b64_tr_b16 v[236:237], v219 offset:0x2000
	ds_read_b64_tr_b16 v[238:239], v219 offset:0x2800
	ds_read_b64_tr_b16 v[240:241], v219 offset:0x3000
	ds_read_b64_tr_b16 v[242:243], v219 offset:0x3800
	s_waitcnt lgkmcnt(4)
	s_nop 0
	v_mfma_f32_32x32x16_bf16 v[58:73], v[0:3], v[98:101], v[58:73]
	ds_read_b64_tr_b16 v[98:99], v219 offset:0x200
	ds_read_b64_tr_b16 v[100:101], v219 offset:0xa00
	v_mfma_f32_32x32x16_bf16 v[58:73], v[4:7], v[102:105], v[58:73]
	ds_read_b64_tr_b16 v[102:103], v219 offset:0x1200
	ds_read_b64_tr_b16 v[104:105], v219 offset:0x1a00
	s_waitcnt lgkmcnt(4)
	v_mfma_f32_32x32x16_bf16 v[58:73], v[74:77], v[236:239], v[58:73]
	ds_read_b64_tr_b16 v[236:237], v219 offset:0x2200
	ds_read_b64_tr_b16 v[238:239], v219 offset:0x2a00
	v_mfma_f32_32x32x16_bf16 v[58:73], v[78:81], v[240:243], v[58:73]
	ds_read_b64_tr_b16 v[240:241], v219 offset:0x3200
	ds_read_b64_tr_b16 v[242:243], v219 offset:0x3a00
	s_waitcnt lgkmcnt(4)
	v_mfma_f32_32x32x16_bf16 v[42:57], v[0:3], v[98:101], v[42:57]
	ds_read_b64_tr_b16 v[98:99], v219 offset:0x400
	ds_read_b64_tr_b16 v[100:101], v219 offset:0xc00
	v_mfma_f32_32x32x16_bf16 v[42:57], v[4:7], v[102:105], v[42:57]
	ds_read_b64_tr_b16 v[102:103], v219 offset:0x1400
	ds_read_b64_tr_b16 v[104:105], v219 offset:0x1c00
	s_waitcnt lgkmcnt(4)
	v_mfma_f32_32x32x16_bf16 v[42:57], v[74:77], v[236:239], v[42:57]
	ds_read_b64_tr_b16 v[236:237], v219 offset:0x2400
	ds_read_b64_tr_b16 v[238:239], v219 offset:0x2c00
	v_mfma_f32_32x32x16_bf16 v[42:57], v[78:81], v[240:243], v[42:57]
	ds_read_b64_tr_b16 v[240:241], v219 offset:0x3400
	ds_read_b64_tr_b16 v[242:243], v219 offset:0x3c00
	s_waitcnt lgkmcnt(4)
	v_mfma_f32_32x32x16_bf16 v[26:41], v[0:3], v[98:101], v[26:41]
	ds_read_b64_tr_b16 v[98:99], v219 offset:0x600
	ds_read_b64_tr_b16 v[100:101], v219 offset:0xe00
	v_mfma_f32_32x32x16_bf16 v[26:41], v[4:7], v[102:105], v[26:41]
	ds_read_b64_tr_b16 v[102:103], v219 offset:0x1600
	ds_read_b64_tr_b16 v[104:105], v219 offset:0x1e00
	s_waitcnt lgkmcnt(4)
	v_mfma_f32_32x32x16_bf16 v[26:41], v[74:77], v[236:239], v[26:41]
	ds_read_b64_tr_b16 v[236:237], v219 offset:0x2600
	ds_read_b64_tr_b16 v[238:239], v219 offset:0x2e00
	v_mfma_f32_32x32x16_bf16 v[26:41], v[78:81], v[240:243], v[26:41]
	ds_read_b64_tr_b16 v[240:241], v219 offset:0x3600
	ds_read_b64_tr_b16 v[242:243], v219 offset:0x3e00
	s_waitcnt lgkmcnt(4)
	v_mfma_f32_32x32x16_bf16 v[10:25], v[0:3], v[98:101], v[10:25]
	s_waitcnt lgkmcnt(0)
	v_mfma_f32_32x32x16_bf16 v[10:25], v[4:7], v[102:105], v[10:25]
	v_mfma_f32_32x32x16_bf16 v[10:25], v[74:77], v[236:239], v[10:25]
	v_mfma_f32_32x32x16_bf16 v[10:25], v[78:81], v[240:243], v[10:25]
	s_waitcnt vmcnt(0)
	s_barrier
	s_cselect_b32 s4, s21, 0x10000000
	s_add_i32 s5, s4, s12
	v_cvt_f32_i32_e32 v0, s27
	s_cmp_lt_i32 s5, 63
	s_cselect_b64 s[10:11], -1, 0
	s_add_i32 s4, s4, s13
	s_cmp_gt_i32 s4, 0
	s_cselect_b64 s[4:5], -1, 0
	v_cndmask_b32_e32 v0, v214, v0, vcc
	s_and_b64 s[4:5], s[10:11], s[4:5]
	v_sub_f32_e32 v0, v176, v0
	s_andn2_b64 vcc, exec, s[4:5]
	s_mov_b64 s[4:5], -1
	s_cbranch_vccz .LBB0_759
	v_cndmask_b32_e64 v2, -v172, v172, s[10:11]
	v_fma_f32 v4, v0, -v2, -v174
	v_fma_f32 v90, 0, v2, v4
	v_add_f32_e32 v91, v2, v4
	v_pk_fma_f32 v[74:75], v[2:3], s[34:35], v[4:5] op_sel_hi:[0,1,0]
	v_pk_fma_f32 v[92:93], v[2:3], s[36:37], v[4:5] op_sel_hi:[0,1,0]
	v_pk_fma_f32 v[76:77], v[2:3], s[38:39], v[4:5] op_sel_hi:[0,1,0]
	v_pk_fma_f32 v[94:95], v[2:3], s[40:41], v[4:5] op_sel_hi:[0,1,0]
	v_pk_fma_f32 v[78:79], v[2:3], s[42:43], v[4:5] op_sel_hi:[0,1,0]
	v_pk_fma_f32 v[96:97], v[2:3], s[44:45], v[4:5] op_sel_hi:[0,1,0]
	v_pk_fma_f32 v[80:81], v[2:3], s[46:47], v[4:5] op_sel_hi:[0,1,0]
	v_pk_fma_f32 v[98:99], v[2:3], s[48:49], v[4:5] op_sel_hi:[0,1,0]
	v_pk_fma_f32 v[82:83], v[2:3], s[50:51], v[4:5] op_sel_hi:[0,1,0]
	v_pk_fma_f32 v[100:101], v[2:3], s[52:53], v[4:5] op_sel_hi:[0,1,0]
	v_pk_fma_f32 v[84:85], v[2:3], s[54:55], v[4:5] op_sel_hi:[0,1,0]
	v_pk_fma_f32 v[102:103], v[2:3], s[56:57], v[4:5] op_sel_hi:[0,1,0]
	v_pk_fma_f32 v[86:87], v[2:3], s[58:59], v[4:5] op_sel_hi:[0,1,0]
	v_fmamk_f32 v88, v2, 0x42680000, v4
	v_pk_fma_f32 v[104:105], v[2:3], s[60:61], v[4:5] op_sel_hi:[0,1,0]
	v_fmac_f32_e32 v4, 0x426c0000, v2
	s_mov_b64 s[4:5], 0
	v_mov_b32_e32 v89, v4

; __device__ __forceinline__ void finishSM(f32x16& p0, f32x16& p1, float& l_reg, bf16x8& pa0, bf16x8& pa1, bf16x8& pa2, bf16x8& pa3) {
; #pragma unroll
;   for (int r = 0; r < 16; ++r) p0[r] = __builtin_amdgcn_exp2f(p0[r]);
; #pragma unroll
;   for (int r = 0; r < 16; ++r) p1[r] = __builtin_amdgcn_exp2f(p1[r]);
;   float ps = 0;
; #pragma unroll
;   for (int r = 0; r < 16; ++r) ps += p0[r];
; #pragma unroll
;   for (int r = 0; r < 16; ++r) ps += p1[r];
;   { auto rr = __builtin_amdgcn_permlane32_swap(__float_as_uint(ps), __float_as_uint(ps), false, false);
;     ps = __uint_as_float(rr[0]) + __uint_as_float(rr[1]); }
;   l_reg += ps;
;     ...
;   PK4(p0, 0, pa0); PK4(p0, 8, pa1); PK4(p1, 0, pa2); PK4(p1, 8, pa3);
;     ...
; }
; template <int MODE>
; __device__ __forceinline__ void qkt(f32x16& p0, f32x16& p1, const bf16* Ks, const bf16x8* qr, int r32, int hi, float dq, float nsl, int side, float mi) {
;   if (MODE == 0) {
;     if (side != 0) {
;       const float sg = side > 0 ? -nsl : nsl, bb = -sg * dq - mi;
; #pragma unroll
;       for (int r = 0; r < 16; ++r) { const float c = (float)((r & 3) + 8 * (r >> 2)); p0[r] = fmaf(c, sg, bb); p1[r] = fmaf(c + 32.f, sg, bb); }
;     } else {
; #pragma unroll
;       for (int r = 0; r < 16; ++r) { const float c = (float)((r & 3) + 8 * (r >> 2)); p0[r] = fmaf(fabsf(dq - c), nsl, -mi); p1[r] = fmaf(fabsf(dq - (c + 32.f)), nsl, -mi); }
;     }
;   } else {
; #pragma unroll
;     for (int r = 0; r < 16; ++r) { const float c = (float)((r & 3) + 8 * (r >> 2)); p0[r] = (r < 8) ? fmaf(fabsf(dq - c), nsl, -mi) : NEGBIG; p1[r] = NEGBIG; }
;   }
; #pragma unroll
;   for (int d0 = 0; d0 < 8; ++d0) {
;     const int ko = r32 * 256 + ((((d0 & 3) * 32 + hi * 16) ^ ((r32 & 7) << 4))) + (d0 >> 2) * 128;
;     bf16x8 b0 = *reinterpret_cast<const bf16x8*>((const char*)Ks + ko);
;     bf16x8 b1 = *reinterpret_cast<const bf16x8*>((const char*)Ks + ko + 8192);
;     p0 = __builtin_amdgcn_mfma_f32_32x32x16_bf16(b0, qr[d0], p0, 0, 0, 0);
;     p1 = __builtin_amdgcn_mfma_f32_32x32x16_bf16(b1, qr[d0], p1, 0, 0, 0); }
; template <int J> ...
;     ...
;     SBAR(); qkt<0>(pA0, pA1, K_lds, qr, r32, hi, TILE_DQ(j + 1), nsl, TILE_SIDE(j + 1), mi);
;     finishSM(pB0, pB1, l_reg, pa0, pa1, pa2, pa3); SBAR();
;     if (SDEPTH == 1 || j + 3 < NT) SLOAD(SE, j + 1 + SDEPTH); SBAR();
;     pv_d0(o, vb0 + (int)SHM_V, pa0, pa1, pa2, pa3); SBAR();
.LBB0_761:
	v_readfirstlane_b32 s92, v248
	s_add_i32 s4, s20, s30
	s_add_i32 s10, s4, 2
	s_ashr_i32 s11, s10, 31
	s_lshl_b64 s[10:11], s[10:11], 18
	s_add_u32 s10, s89, s10
	s_addc_u32 s11, s24, s11
	s_add_i32 s5, s30, 2
	s_cmp_lt_i32 s5, s15
	s_cselect_b32 s10, s10, s16
	s_cselect_b32 s11, s11, s1
	s_add_i32 s4, s4, 1
	s_ashr_i32 s5, s4, 31
	s_lshl_b64 s[4:5], s[4:5], 18
	s_add_u32 s4, s0, s4
	s_addc_u32 s5, s25, s5
	s_add_i32 m0, s92, 0xc000
	s_nop 0
	global_load_lds_dwordx4 v245, s[10:11]
	s_add_i32 m0, s92, 0xc400
	s_nop 0
	global_load_lds_dwordx4 v246, s[10:11]
	s_add_i32 m0, s92, 0x0
	s_nop 0
	global_load_lds_dwordx4 v247, s[4:5]
	s_add_i32 m0, s92, 0x380
	s_nop 0
	global_load_lds_dwordx4 v247, s[4:5] offset:128
	v_add_f32_e32 v0, v233, v234
	v_add_f32_e32 v173, v226, v0
	ds_read_b128 v[0:3], v229 offset:32768
	ds_read_b128 v[4:7], v229 offset:40960
	v_exp_f32_e32 v106, v106
	v_exp_f32_e32 v107, v107
	s_waitcnt lgkmcnt(1)
	v_mfma_f32_32x32x16_bf16 v[90:105], v[0:3], v[158:161], v[90:105]
	v_exp_f32_e32 v108, v108
	v_exp_f32_e32 v109, v109
	v_exp_f32_e32 v110, v110
	v_exp_f32_e32 v111, v111
	v_exp_f32_e32 v112, v112
	v_exp_f32_e32 v113, v113
	v_exp_f32_e32 v114, v114
	s_waitcnt lgkmcnt(0)
	v_mfma_f32_32x32x16_bf16 v[74:89], v[4:7], v[158:161], v[74:89]
	ds_read_b128 v[0:3], v230 offset:32768
	ds_read_b128 v[4:7], v230 offset:40960
	v_exp_f32_e32 v115, v115
	v_exp_f32_e32 v116, v116
	v_exp_f32_e32 v117, v117
	v_exp_f32_e32 v118, v118
	v_exp_f32_e32 v119, v119
	v_exp_f32_e32 v120, v120
	s_waitcnt lgkmcnt(1)
	v_mfma_f32_32x32x16_bf16 v[90:105], v[0:3], v[154:157], v[90:105]
	v_exp_f32_e32 v121, v121
	s_waitcnt lgkmcnt(0)
	v_mfma_f32_32x32x16_bf16 v[74:89], v[4:7], v[154:157], v[74:89]
	ds_read_b128 v[0:3], v231 offset:32768
	ds_read_b128 v[4:7], v231 offset:40960
	s_waitcnt lgkmcnt(1)
	v_mfma_f32_32x32x16_bf16 v[90:105], v[0:3], v[150:153], v[90:105]
	s_waitcnt lgkmcnt(0)
	v_mfma_f32_32x32x16_bf16 v[74:89], v[4:7], v[150:153], v[74:89]
	ds_read_b128 v[0:3], v232 offset:32768
	ds_read_b128 v[4:7], v232 offset:40960
	s_waitcnt lgkmcnt(1)
	v_mfma_f32_32x32x16_bf16 v[90:105], v[0:3], v[146:149], v[90:105]
	s_waitcnt lgkmcnt(0)
	v_mfma_f32_32x32x16_bf16 v[74:89], v[4:7], v[146:149], v[74:89]
	ds_read_b128 v[0:3], v229 offset:32896
	ds_read_b128 v[4:7], v229 offset:41088
	s_waitcnt lgkmcnt(1)
	v_mfma_f32_32x32x16_bf16 v[90:105], v[0:3], v[142:145], v[90:105]
	s_waitcnt lgkmcnt(0)
	v_mfma_f32_32x32x16_bf16 v[74:89], v[4:7], v[142:145], v[74:89]
	ds_read_b128 v[0:3], v230 offset:32896
	ds_read_b128 v[4:7], v230 offset:41088
	s_waitcnt lgkmcnt(1)
	v_mfma_f32_32x32x16_bf16 v[90:105], v[0:3], v[138:141], v[90:105]
	s_waitcnt lgkmcnt(0)
	v_mfma_f32_32x32x16_bf16 v[74:89], v[4:7], v[138:141], v[74:89]
	ds_read_b128 v[0:3], v231 offset:32896
	ds_read_b128 v[4:7], v231 offset:41088
	s_waitcnt lgkmcnt(1)
	v_mfma_f32_32x32x16_bf16 v[90:105], v[0:3], v[166:169], v[90:105]
	s_waitcnt lgkmcnt(0)
	v_mfma_f32_32x32x16_bf16 v[74:89], v[4:7], v[166:169], v[74:89]
	ds_read_b128 v[0:3], v232 offset:32896
	ds_read_b128 v[4:7], v232 offset:41088
	s_waitcnt lgkmcnt(1)
	v_mfma_f32_32x32x16_bf16 v[90:105], v[0:3], v[162:165], v[90:105]
	v_exp_f32_e32 v0, v122
	v_exp_f32_e32 v1, v123
	v_exp_f32_e32 v2, v124
	v_exp_f32_e32 v3, v125
	v_exp_f32_e32 v122, v130
	v_add_f32_e32 v130, 0, v0
	v_add_f32_e32 v130, v1, v130
	s_waitcnt lgkmcnt(0)
	v_mfma_f32_32x32x16_bf16 v[74:89], v[4:7], v[162:165], v[74:89]
	v_exp_f32_e32 v4, v126
	v_exp_f32_e32 v5, v127
	v_exp_f32_e32 v6, v128
	v_add_f32_e32 v130, v2, v130
	v_exp_f32_e32 v7, v129
	v_add_f32_e32 v130, v3, v130
	v_add_f32_e32 v130, v4, v130
	v_exp_f32_e32 v123, v131
	v_add_f32_e32 v130, v5, v130
	v_exp_f32_e32 v124, v132
	v_add_f32_e32 v130, v6, v130
	v_exp_f32_e32 v125, v133
	v_add_f32_e32 v130, v7, v130
	v_exp_f32_e32 v126, v134
	v_add_f32_e32 v130, v122, v130
	v_exp_f32_e32 v127, v135
	v_add_f32_e32 v130, v123, v130
	v_exp_f32_e32 v128, v136
	v_add_f32_e32 v130, v124, v130
	v_exp_f32_e32 v129, v137
	v_add_f32_e32 v130, v125, v130
	v_add_f32_e32 v130, v126, v130
	v_add_f32_e32 v130, v127, v130
	v_add_f32_e32 v130, v128, v130
	v_add_f32_e32 v130, v129, v130
	v_add_f32_e32 v130, v106, v130
	v_add_f32_e32 v130, v107, v130
	v_add_f32_e32 v130, v108, v130
	v_add_f32_e32 v130, v109, v130
	v_add_f32_e32 v130, v110, v130
	v_add_f32_e32 v130, v111, v130
	v_add_f32_e32 v130, v112, v130
	v_add_f32_e32 v130, v113, v130
	v_add_f32_e32 v130, v114, v130
	v_add_f32_e32 v130, v115, v130
	v_add_f32_e32 v130, v116, v130
	v_add_f32_e32 v130, v117, v130
	v_add_f32_e32 v130, v118, v130
	v_add_f32_e32 v130, v119, v130
	v_add_f32_e32 v130, v120, v130
	v_add_f32_e32 v130, v121, v130
	v_mov_b32_e32 v131, v130
	s_nop 1
	v_permlane32_swap_b32_e32 v130, v131
	v_add_f32_e32 v130, v130, v131
	v_add_f32_e32 v226, v173, v130
	v_cvt_pk_bf16_f32 v0, v0, v1
	v_cvt_pk_bf16_f32 v1, v2, v3
	v_cvt_pk_bf16_f32 v2, v4, v5
	v_cvt_pk_bf16_f32 v3, v6, v7
	v_cvt_pk_bf16_f32 v4, v122, v123
	v_cvt_pk_bf16_f32 v5, v124, v125
	v_cvt_pk_bf16_f32 v6, v126, v127
	v_cvt_pk_bf16_f32 v7, v128, v129
	v_cvt_pk_bf16_f32 v106, v106, v107
	v_cvt_pk_bf16_f32 v107, v108, v109
	v_cvt_pk_bf16_f32 v108, v110, v111
	v_cvt_pk_bf16_f32 v109, v112, v113
	v_cvt_pk_bf16_f32 v110, v114, v115
	v_cvt_pk_bf16_f32 v111, v116, v117
	v_cvt_pk_bf16_f32 v112, v118, v119
	v_cvt_pk_bf16_f32 v113, v120, v121
	s_nop 0
	v_permlane32_swap_b32_e32 v0, v2
	v_permlane32_swap_b32_e32 v1, v3
	v_permlane32_swap_b32_e32 v4, v6
	v_permlane32_swap_b32_e32 v5, v7
	v_permlane32_swap_b32_e32 v106, v108
	v_permlane32_swap_b32_e32 v107, v109
	v_permlane32_swap_b32_e32 v110, v112
	v_permlane32_swap_b32_e32 v111, v113
	s_add_i32 s10, s3, 2
	s_ashr_i32 s11, s10, 31
	s_add_i32 s4, s30, 2
	s_lshl_b64 s[10:11], s[10:11], 18
	s_add_u32 s3, s89, s10
	s_addc_u32 s5, s24, s11
	s_add_u32 s9, s0, s10
	s_addc_u32 s31, s25, s11
	s_cmp_lt_i32 s4, s15
	s_cselect_b32 s11, s5, s1
	s_cselect_b32 s10, s3, s16
	s_cselect_b32 s93, s31, s29
	s_cselect_b32 s92, s9, s28
	s_waitcnt lgkmcnt(0)
; #define SBAR() __builtin_amdgcn_sched_barrier(0)
; #define PV_WAIT4() do { asm volatile("s_waitcnt lgkmcnt(4)" ::: "memory"); SBAR(); } while (0)
; #define PV_WAIT0() do { asm volatile("s_waitcnt lgkmcnt(0)" ::: "memory"); SBAR(); } while (0)
; #define PV_MM(od, pX, pY, g) do { od = __builtin_amdgcn_mfma_f32_32x32x16_bf16(pX, PK(g.l0, g.h0), od, 0, 0, 0); od = __builtin_amdgcn_mfma_f32_32x32x16_bf16(pY, PK(g.l1, g.h1), od, 0, 0, 0); } while (0)
; #define SWRITE(b, i) do { *(bf16x8*)((char*)V_lds + (b) * SHM_V + vst0) = sr_[i].vs0;          \
;     *(bf16x8*)((char*)V_lds + (b) * SHM_V + vst1) = sr_[i].vs1; int kc = sc * 2;               \
;     *(bf16x8*)((char*)K_lds + (b) * SHM_K + KSWZ(sr, kc)) = sr_[i].ks0;                       \
;     *(bf16x8*)((char*)K_lds + (b) * SHM_K + KSWZ(32 + sr, kc)) = sr_[i].ks1; } while (0)
; #define SWAIT() do { if constexpr (SDEPTH == 2) asm volatile("s_waitcnt vmcnt(4)" ::: "memory"); else asm volatile("s_waitcnt vmcnt(0)" ::: "memory"); } while (0)
; __device__ __forceinline__ void pv_d0(f32x16* o, int vb, bf16x8 pa0, bf16x8 pa1, bf16x8 pa2, bf16x8 pa3) {
;   asm volatile("s_waitcnt lgkmcnt(0)" ::: "memory");
;   VG a0 = pv_reads<0, 0>(vb), b0 = pv_reads<0, 2>(vb);
;   PV_WAIT4(); PV_MM(o[0], pa0, pa1, a0); VG a1 = pv_reads<1, 0>(vb);
;   PV_WAIT4(); PV_MM(o[0], pa2, pa3, b0); VG b1 = pv_reads<1, 2>(vb);
;   PV_WAIT4(); PV_MM(o[1], pa0, pa1, a1); VG a2 = pv_reads<2, 0>(vb);
;   PV_WAIT4(); PV_MM(o[1], pa2, pa3, b1); VG b2 = pv_reads<2, 2>(vb);
;   PV_WAIT4(); PV_MM(o[2], pa0, pa1, a2); VG a3 = pv_reads<3, 0>(vb);
;   PV_WAIT4(); PV_MM(o[2], pa2, pa3, b2); VG b3 = pv_reads<3, 2>(vb);
;   PV_WAIT4(); PV_MM(o[3], pa0, pa1, a3);
;   PV_WAIT0(); PV_MM(o[3], pa2, pa3, b3);
; }
; template <int J> ...
;     ...
;     pv_d0(o, vb0 + (int)SHM_V, pa0, pa1, pa2, pa3); SBAR();
;     __syncthreads(); SWAIT(); SWRITE(1, SO);
;     __syncthreads();
;   }
	ds_read_b64_tr_b16 v[130:131], v228 offset:0
	ds_read_b64_tr_b16 v[132:133], v228 offset:0x800
	ds_read_b64_tr_b16 v[134:135], v228 offset:0x1000
	ds_read_b64_tr_b16 v[136:137], v228 offset:0x1800
	ds_read_b64_tr_b16 v[234:235], v228 offset:0x2000
	ds_read_b64_tr_b16 v[236:237], v228 offset:0x2800
	ds_read_b64_tr_b16 v[238:239], v228 offset:0x3000
	ds_read_b64_tr_b16 v[240:241], v228 offset:0x3800
	s_waitcnt lgkmcnt(4)
	s_nop 0
	v_mfma_f32_32x32x16_bf16 v[58:73], v[0:3], v[130:133], v[58:73]
	ds_read_b64_tr_b16 v[130:131], v228 offset:0x200
	ds_read_b64_tr_b16 v[132:133], v228 offset:0xa00
	v_mfma_f32_32x32x16_bf16 v[58:73], v[4:7], v[134:137], v[58:73]
	ds_read_b64_tr_b16 v[134:135], v228 offset:0x1200
	ds_read_b64_tr_b16 v[136:137], v228 offset:0x1a00
	s_waitcnt lgkmcnt(4)
	v_mfma_f32_32x32x16_bf16 v[58:73], v[106:109], v[234:237], v[58:73]
	ds_read_b64_tr_b16 v[234:235], v228 offset:0x2200
	ds_read_b64_tr_b16 v[236:237], v228 offset:0x2a00
	v_mfma_f32_32x32x16_bf16 v[58:73], v[110:113], v[238:241], v[58:73]
	ds_read_b64_tr_b16 v[238:239], v228 offset:0x3200
	ds_read_b64_tr_b16 v[240:241], v228 offset:0x3a00
	s_waitcnt lgkmcnt(4)
	v_mfma_f32_32x32x16_bf16 v[42:57], v[0:3], v[130:133], v[42:57]
	ds_read_b64_tr_b16 v[130:131], v228 offset:0x400
	ds_read_b64_tr_b16 v[132:133], v228 offset:0xc00
	v_mfma_f32_32x32x16_bf16 v[42:57], v[4:7], v[134:137], v[42:57]
	ds_read_b64_tr_b16 v[134:135], v228 offset:0x1400
	ds_read_b64_tr_b16 v[136:137], v228 offset:0x1c00
	s_waitcnt lgkmcnt(4)
	v_mfma_f32_32x32x16_bf16 v[42:57], v[106:109], v[234:237], v[42:57]
	ds_read_b64_tr_b16 v[234:235], v228 offset:0x2400
	ds_read_b64_tr_b16 v[236:237], v228 offset:0x2c00
	v_mfma_f32_32x32x16_bf16 v[42:57], v[110:113], v[238:241], v[42:57]
	ds_read_b64_tr_b16 v[238:239], v228 offset:0x3400
	ds_read_b64_tr_b16 v[240:241], v228 offset:0x3c00
	s_waitcnt lgkmcnt(4)
	v_mfma_f32_32x32x16_bf16 v[26:41], v[0:3], v[130:133], v[26:41]
	ds_read_b64_tr_b16 v[130:131], v228 offset:0x600
	ds_read_b64_tr_b16 v[132:133], v228 offset:0xe00
	v_mfma_f32_32x32x16_bf16 v[26:41], v[4:7], v[134:137], v[26:41]
	ds_read_b64_tr_b16 v[134:135], v228 offset:0x1600
	ds_read_b64_tr_b16 v[136:137], v228 offset:0x1e00
	s_waitcnt lgkmcnt(4)
	v_mfma_f32_32x32x16_bf16 v[26:41], v[106:109], v[234:237], v[26:41]
	ds_read_b64_tr_b16 v[234:235], v228 offset:0x2600
	ds_read_b64_tr_b16 v[236:237], v228 offset:0x2e00
	v_mfma_f32_32x32x16_bf16 v[26:41], v[110:113], v[238:241], v[26:41]
	ds_read_b64_tr_b16 v[238:239], v228 offset:0x3600
	ds_read_b64_tr_b16 v[240:241], v228 offset:0x3e00
	s_waitcnt lgkmcnt(4)
	v_mfma_f32_32x32x16_bf16 v[10:25], v[0:3], v[130:133], v[10:25]
	s_waitcnt lgkmcnt(0)
	v_mfma_f32_32x32x16_bf16 v[10:25], v[4:7], v[134:137], v[10:25]
	v_mfma_f32_32x32x16_bf16 v[10:25], v[106:109], v[234:237], v[10:25]
	v_mfma_f32_32x32x16_bf16 v[10:25], v[110:113], v[238:241], v[10:25]
	s_addk_i32 s21, 0xff80
	s_addk_i32 s27, 0x80
	s_add_i32 s3, s30, 3
	s_cmp_ge_i32 s3, s14
	s_waitcnt vmcnt(0)
	s_barrier
	s_cbranch_scc1 .Lmy_i2_exit
	s_mov_b32 s30, s4
	s_branch .LBB0_753
.Lmy_i2_exit:
	v_readfirstlane_b32 s92, v248
	s_add_i32 s4, s20, s14
	s_add_i32 s4, s4, -1
	s_ashr_i32 s5, s4, 31
	s_lshl_b64 s[4:5], s[4:5], 18
	s_add_u32 s4, s0, s4
	s_addc_u32 s5, s25, s5
	s_cmp_gt_i32 s14, s15
	s_cselect_b32 s4, s28, s4
	s_cselect_b32 s5, s29, s5
	s_add_i32 m0, s92, 0x4000
	s_nop 0
	global_load_lds_dwordx4 v247, s[4:5]
	s_add_i32 m0, s92, 0x4380
	s_nop 0
	global_load_lds_dwordx4 v247, s[4:5] offset:128
	s_branch .LBB0_764

; #define SBAR() __builtin_amdgcn_sched_barrier(0)
; __device__ __forceinline__ void finishSM(f32x16& p0, f32x16& p1, float& l_reg, bf16x8& pa0, bf16x8& pa1, bf16x8& pa2, bf16x8& pa3) {
; #pragma unroll
;   for (int r = 0; r < 16; ++r) p0[r] = __builtin_amdgcn_exp2f(p0[r]);
; #pragma unroll
;   for (int r = 0; r < 16; ++r) p1[r] = __builtin_amdgcn_exp2f(p1[r]);
;   float ps = 0;
; #pragma unroll
;   for (int r = 0; r < 16; ++r) ps += p0[r];
; #pragma unroll
;   for (int r = 0; r < 16; ++r) ps += p1[r];
;   { auto rr = __builtin_amdgcn_permlane32_swap(__float_as_uint(ps), __float_as_uint(ps), false, false);
;     ps = __uint_as_float(rr[0]) + __uint_as_float(rr[1]); }
;   l_reg += ps;
;     ...
;   PK4(p0, 0, pa0); PK4(p0, 8, pa1); PK4(p1, 0, pa2); PK4(p1, 8, pa3);
;     ...
; }
; template <int MODE>
; __device__ __forceinline__ void qkt(f32x16& p0, f32x16& p1, const bf16* Ks, const bf16x8* qr, int r32, int hi, float dq, float nsl, int side, float mi) {
;   if (MODE == 0) {
;     if (side != 0) {
;       const float sg = side > 0 ? -nsl : nsl, bb = -sg * dq - mi;
; #pragma unroll
;       for (int r = 0; r < 16; ++r) { const float c = (float)((r & 3) + 8 * (r >> 2)); p0[r] = fmaf(c, sg, bb); p1[r] = fmaf(c + 32.f, sg, bb); }
;     } else {
; #pragma unroll
;       for (int r = 0; r < 16; ++r) { const float c = (float)((r & 3) + 8 * (r >> 2)); p0[r] = fmaf(fabsf(dq - c), nsl, -mi); p1[r] = fmaf(fabsf(dq - (c + 32.f)), nsl, -mi); }
;     }
;   } else {
; #pragma unroll
;     for (int r = 0; r < 16; ++r) { const float c = (float)((r & 3) + 8 * (r >> 2)); p0[r] = (r < 8) ? fmaf(fabsf(dq - c), nsl, -mi) : NEGBIG; p1[r] = NEGBIG; }
;   }
; #pragma unroll
;   for (int d0 = 0; d0 < 8; ++d0) {
;     const int ko = r32 * 256 + ((((d0 & 3) * 32 + hi * 16) ^ ((r32 & 7) << 4))) + (d0 >> 2) * 128;
;     bf16x8 b0 = *reinterpret_cast<const bf16x8*>((const char*)Ks + ko);
;     bf16x8 b1 = *reinterpret_cast<const bf16x8*>((const char*)Ks + ko + 8192);
;     p0 = __builtin_amdgcn_mfma_f32_32x32x16_bf16(b0, qr[d0], p0, 0, 0, 0);
;     p1 = __builtin_amdgcn_mfma_f32_32x32x16_bf16(b1, qr[d0], p1, 0, 0, 0); }
; template <int J> ...
;     ...
;   SBAR(); qkt<0>(pB0, pB1, (bf16*)((char*)K_lds + SHM_K), qr, r32, hi, TILE_DQ(NT - 1), nsl, TILE_SIDE(NT - 1), mi);
;   finishSM(pA0, pA1, l_reg, pa0, pa1, pa2, pa3); SBAR();
;   pv_d0(o, vb0, pa0, pa1, pa2, pa3); SBAR();
.LBB0_768:
	s_movk_i32 s1, 0x70
	v_bitop3_b32 v0, v170, v222, s1 bitop3:0x78
	v_add3_u32 v172, 0, v0, v227
	ds_read_b128 v[0:3], v172 offset:49152
	ds_read_b128 v[4:7], v172 offset:57344
	s_movk_i32 s1, 0x60
	v_exp_f32_e32 v81, v81
	v_exp_f32_e32 v82, v82
	s_waitcnt lgkmcnt(1)
	v_mfma_f32_32x32x16_bf16 v[122:137], v[0:3], v[158:161], v[122:137]
	v_bitop3_b32 v0, v170, v220, 32 bitop3:0x36
	v_exp_f32_e32 v83, v83
	v_exp_f32_e32 v84, v84
	v_exp_f32_e32 v85, v85
	v_exp_f32_e32 v86, v86
	v_exp_f32_e32 v87, v87
	v_exp_f32_e32 v88, v88
	s_waitcnt lgkmcnt(0)
	v_mfma_f32_32x32x16_bf16 v[106:121], v[4:7], v[158:161], v[106:121]
	v_add3_u32 v158, 0, v0, v227
	ds_read_b128 v[0:3], v158 offset:49152
	ds_read_b128 v[4:7], v158 offset:57344
	v_exp_f32_e32 v89, v89
	s_and_b32 s0, s7, 0x3fffffc0
	s_lshl_b32 s0, s0, 2
	s_add_i32 s0, s0, 0
	s_add_i32 s0, s0, 0x10000
	s_waitcnt lgkmcnt(1)
	v_mfma_f32_32x32x16_bf16 v[122:137], v[0:3], v[154:157], v[122:137]
	v_bitop3_b32 v0, v170, v220, 64 bitop3:0x36
	s_waitcnt lgkmcnt(0)
	v_mfma_f32_32x32x16_bf16 v[106:121], v[4:7], v[154:157], v[106:121]
	v_add3_u32 v154, 0, v0, v227
	ds_read_b128 v[0:3], v154 offset:49152
	ds_read_b128 v[4:7], v154 offset:57344
	s_waitcnt lgkmcnt(1)
	v_mfma_f32_32x32x16_bf16 v[122:137], v[0:3], v[150:153], v[122:137]
	v_bitop3_b32 v0, v170, v220, s1 bitop3:0x36
	s_waitcnt lgkmcnt(0)
	v_mfma_f32_32x32x16_bf16 v[106:121], v[4:7], v[150:153], v[106:121]
	v_add3_u32 v150, 0, v0, v227
	ds_read_b128 v[0:3], v150 offset:49152
	ds_read_b128 v[4:7], v150 offset:57344
	s_waitcnt lgkmcnt(1)
	v_mfma_f32_32x32x16_bf16 v[122:137], v[0:3], v[146:149], v[122:137]
	s_waitcnt lgkmcnt(0)
	v_mfma_f32_32x32x16_bf16 v[106:121], v[4:7], v[146:149], v[106:121]
	ds_read_b128 v[0:3], v172 offset:49280
	ds_read_b128 v[4:7], v172 offset:57472
	s_waitcnt lgkmcnt(1)
	v_mfma_f32_32x32x16_bf16 v[122:137], v[0:3], v[142:145], v[122:137]
	s_waitcnt lgkmcnt(0)
	v_mfma_f32_32x32x16_bf16 v[106:121], v[4:7], v[142:145], v[106:121]
	ds_read_b128 v[0:3], v158 offset:49280
	ds_read_b128 v[4:7], v158 offset:57472
	s_waitcnt lgkmcnt(1)
	v_mfma_f32_32x32x16_bf16 v[122:137], v[0:3], v[138:141], v[122:137]
	s_waitcnt lgkmcnt(0)
	v_mfma_f32_32x32x16_bf16 v[106:121], v[4:7], v[138:141], v[106:121]
	ds_read_b128 v[0:3], v154 offset:49280
	ds_read_b128 v[4:7], v154 offset:57472
	v_exp_f32_e32 v138, v79
	v_exp_f32_e32 v139, v80
	s_waitcnt lgkmcnt(1)
	v_mfma_f32_32x32x16_bf16 v[122:137], v[0:3], v[166:169], v[122:137]
	s_waitcnt lgkmcnt(0)
	v_mfma_f32_32x32x16_bf16 v[106:121], v[4:7], v[166:169], v[106:121]
	ds_read_b128 v[0:3], v150 offset:49280
	ds_read_b128 v[4:7], v150 offset:57472
	s_waitcnt lgkmcnt(1)
	v_mfma_f32_32x32x16_bf16 v[122:137], v[0:3], v[162:165], v[122:137]
	v_exp_f32_e32 v1, v90
	v_exp_f32_e32 v3, v91
	v_exp_f32_e32 v90, v95
	v_exp_f32_e32 v91, v96
	v_add_f32_e32 v0, 0, v1
	v_add_f32_e32 v0, v3, v0
	v_exp_f32_e32 v95, v100
	s_waitcnt lgkmcnt(0)
	v_mfma_f32_32x32x16_bf16 v[106:121], v[4:7], v[162:165], v[106:121]
	v_exp_f32_e32 v5, v92
	v_exp_f32_e32 v6, v93
	v_exp_f32_e32 v7, v94
	v_exp_f32_e32 v92, v97
	v_add_f32_e32 v0, v5, v0
	v_add_f32_e32 v0, v6, v0
	v_exp_f32_e32 v93, v98
	v_add_f32_e32 v0, v7, v0
	v_exp_f32_e32 v94, v99
	v_add_f32_e32 v0, v90, v0
	v_add_f32_e32 v0, v91, v0
	v_exp_f32_e32 v96, v101
	v_add_f32_e32 v0, v92, v0
	v_exp_f32_e32 v97, v102
	v_add_f32_e32 v0, v93, v0
	v_exp_f32_e32 v98, v103
	v_add_f32_e32 v0, v94, v0
	v_exp_f32_e32 v99, v104
	v_add_f32_e32 v0, v95, v0
	v_exp_f32_e32 v100, v105
	v_add_f32_e32 v0, v96, v0
	v_exp_f32_e32 v101, v74
	v_add_f32_e32 v0, v97, v0
	v_exp_f32_e32 v102, v75
	v_add_f32_e32 v0, v98, v0
	v_exp_f32_e32 v103, v76
	v_add_f32_e32 v0, v99, v0
	v_exp_f32_e32 v104, v77
	v_add_f32_e32 v0, v100, v0
	v_exp_f32_e32 v105, v78
	v_add_f32_e32 v0, v101, v0
	v_add_f32_e32 v0, v102, v0
	v_add_f32_e32 v0, v103, v0
	v_add_f32_e32 v0, v104, v0
	v_add_f32_e32 v0, v105, v0
	v_add_f32_e32 v0, v138, v0
	v_add_f32_e32 v0, v139, v0
	v_add_f32_e32 v0, v81, v0
	v_add_f32_e32 v0, v82, v0
	v_add_f32_e32 v0, v83, v0
	v_add_f32_e32 v0, v84, v0
	v_add_f32_e32 v0, v85, v0
	v_add_f32_e32 v0, v86, v0
	v_add_f32_e32 v0, v87, v0
	v_add_f32_e32 v0, v88, v0
	v_add_f32_e32 v0, v89, v0
	v_mov_b32_e32 v2, v0
	s_nop 1
	v_permlane32_swap_b32_e32 v0, v2
	v_cvt_pk_bf16_f32 v4, v1, v3
	v_cvt_pk_bf16_f32 v5, v5, v6
	v_cvt_pk_bf16_f32 v6, v7, v90
	v_cvt_pk_bf16_f32 v7, v91, v92
	v_cvt_pk_bf16_f32 v74, v93, v94
	v_cvt_pk_bf16_f32 v75, v95, v96
	v_cvt_pk_bf16_f32 v76, v97, v98
	v_cvt_pk_bf16_f32 v77, v99, v100
	v_cvt_pk_bf16_f32 v78, v101, v102
	v_cvt_pk_bf16_f32 v79, v103, v104
	v_cvt_pk_bf16_f32 v80, v105, v138
	v_cvt_pk_bf16_f32 v81, v139, v81
	v_cvt_pk_bf16_f32 v82, v82, v83
	v_cvt_pk_bf16_f32 v83, v84, v85
	v_cvt_pk_bf16_f32 v84, v86, v87
	v_cvt_pk_bf16_f32 v85, v88, v89
	s_nop 0
	v_permlane32_swap_b32_e32 v4, v6
	v_permlane32_swap_b32_e32 v5, v7
	v_permlane32_swap_b32_e32 v74, v76
	v_permlane32_swap_b32_e32 v75, v77
	v_permlane32_swap_b32_e32 v78, v80
	v_permlane32_swap_b32_e32 v79, v81
	v_permlane32_swap_b32_e32 v82, v84
	v_permlane32_swap_b32_e32 v83, v85
	s_waitcnt lgkmcnt(0)
	ds_read_b64_tr_b16 v[86:87], v219 offset:0
	ds_read_b64_tr_b16 v[88:89], v219 offset:0x800
	ds_read_b64_tr_b16 v[90:91], v219 offset:0x1000
	ds_read_b64_tr_b16 v[92:93], v219 offset:0x1800
	ds_read_b64_tr_b16 v[94:95], v219 offset:0x2000
	ds_read_b64_tr_b16 v[96:97], v219 offset:0x2800
	ds_read_b64_tr_b16 v[98:99], v219 offset:0x3000
	ds_read_b64_tr_b16 v[100:101], v219 offset:0x3800
	s_waitcnt lgkmcnt(4)
; #define SBAR() __builtin_amdgcn_sched_barrier(0)
; #define PV_WAIT4() do { asm volatile("s_waitcnt lgkmcnt(4)" ::: "memory"); SBAR(); } while (0)
; #define PV_WAIT0() do { asm volatile("s_waitcnt lgkmcnt(0)" ::: "memory"); SBAR(); } while (0)
; #define PV_MM(od, pX, pY, g) do { od = __builtin_amdgcn_mfma_f32_32x32x16_bf16(pX, PK(g.l0, g.h0), od, 0, 0, 0); od = __builtin_amdgcn_mfma_f32_32x32x16_bf16(pY, PK(g.l1, g.h1), od, 0, 0, 0); } while (0)
; __device__ __forceinline__ void pv_d0(f32x16* o, int vb, bf16x8 pa0, bf16x8 pa1, bf16x8 pa2, bf16x8 pa3) {
;   asm volatile("s_waitcnt lgkmcnt(0)" ::: "memory");
;   VG a0 = pv_reads<0, 0>(vb), b0 = pv_reads<0, 2>(vb);
;   PV_WAIT4(); PV_MM(o[0], pa0, pa1, a0); VG a1 = pv_reads<1, 0>(vb);
;   PV_WAIT4(); PV_MM(o[0], pa2, pa3, b0); VG b1 = pv_reads<1, 2>(vb);
;   PV_WAIT4(); PV_MM(o[1], pa0, pa1, a1); VG a2 = pv_reads<2, 0>(vb);
;   PV_WAIT4(); PV_MM(o[1], pa2, pa3, b1); VG b2 = pv_reads<2, 2>(vb);
;   PV_WAIT4(); PV_MM(o[2], pa0, pa1, a2); VG a3 = pv_reads<3, 0>(vb);
;   PV_WAIT4(); PV_MM(o[2], pa2, pa3, b2); VG b3 = pv_reads<3, 2>(vb);
;   PV_WAIT4(); PV_MM(o[3], pa0, pa1, a3);
;   PV_WAIT0(); PV_MM(o[3], pa2, pa3, b3);
; }
; template <int J> ...
;     ...
;   pv_d0(o, vb0, pa0, pa1, pa2, pa3); SBAR();
;   __syncthreads();
;   finishSM(pB0, pB1, l_reg, pa0, pa1, pa2, pa3); SBAR();
	s_nop 0
	v_mfma_f32_32x32x16_bf16 v[58:73], v[4:7], v[86:89], v[58:73]
	ds_read_b64_tr_b16 v[86:87], v219 offset:0x200
	ds_read_b64_tr_b16 v[88:89], v219 offset:0xa00
	v_mfma_f32_32x32x16_bf16 v[58:73], v[74:77], v[90:93], v[58:73]
	ds_read_b64_tr_b16 v[90:91], v219 offset:0x1200
	ds_read_b64_tr_b16 v[92:93], v219 offset:0x1a00
	s_waitcnt lgkmcnt(4)
	v_mfma_f32_32x32x16_bf16 v[58:73], v[78:81], v[94:97], v[58:73]
	ds_read_b64_tr_b16 v[94:95], v219 offset:0x2200
	ds_read_b64_tr_b16 v[96:97], v219 offset:0x2a00
	v_mfma_f32_32x32x16_bf16 v[58:73], v[82:85], v[98:101], v[58:73]
	ds_read_b64_tr_b16 v[98:99], v219 offset:0x3200
	ds_read_b64_tr_b16 v[100:101], v219 offset:0x3a00
	s_waitcnt lgkmcnt(4)
	v_mfma_f32_32x32x16_bf16 v[42:57], v[4:7], v[86:89], v[42:57]
	ds_read_b64_tr_b16 v[86:87], v219 offset:0x400
	ds_read_b64_tr_b16 v[88:89], v219 offset:0xc00
	v_mfma_f32_32x32x16_bf16 v[42:57], v[74:77], v[90:93], v[42:57]
	ds_read_b64_tr_b16 v[90:91], v219 offset:0x1400
	ds_read_b64_tr_b16 v[92:93], v219 offset:0x1c00
	s_waitcnt lgkmcnt(4)
	v_mfma_f32_32x32x16_bf16 v[42:57], v[78:81], v[94:97], v[42:57]
	ds_read_b64_tr_b16 v[94:95], v219 offset:0x2400
	ds_read_b64_tr_b16 v[96:97], v219 offset:0x2c00
	v_mfma_f32_32x32x16_bf16 v[42:57], v[82:85], v[98:101], v[42:57]
	ds_read_b64_tr_b16 v[98:99], v219 offset:0x3400
	ds_read_b64_tr_b16 v[100:101], v219 offset:0x3c00
	s_waitcnt lgkmcnt(4)
	v_mfma_f32_32x32x16_bf16 v[26:41], v[4:7], v[86:89], v[26:41]
	ds_read_b64_tr_b16 v[86:87], v219 offset:0x600
	ds_read_b64_tr_b16 v[88:89], v219 offset:0xe00
	v_mfma_f32_32x32x16_bf16 v[26:41], v[74:77], v[90:93], v[26:41]
	ds_read_b64_tr_b16 v[90:91], v219 offset:0x1600
	ds_read_b64_tr_b16 v[92:93], v219 offset:0x1e00
	s_waitcnt lgkmcnt(4)
	v_mfma_f32_32x32x16_bf16 v[26:41], v[78:81], v[94:97], v[26:41]
	ds_read_b64_tr_b16 v[94:95], v219 offset:0x2600
	ds_read_b64_tr_b16 v[96:97], v219 offset:0x2e00
	v_mfma_f32_32x32x16_bf16 v[26:41], v[82:85], v[98:101], v[26:41]
	ds_read_b64_tr_b16 v[98:99], v219 offset:0x3600
	ds_read_b64_tr_b16 v[100:101], v219 offset:0x3e00
	s_waitcnt lgkmcnt(4)
	v_mfma_f32_32x32x16_bf16 v[10:25], v[4:7], v[86:89], v[10:25]
	s_waitcnt lgkmcnt(0)
	v_mfma_f32_32x32x16_bf16 v[10:25], v[74:77], v[90:93], v[10:25]
	v_mfma_f32_32x32x16_bf16 v[10:25], v[78:81], v[94:97], v[10:25]
	v_mfma_f32_32x32x16_bf16 v[10:25], v[82:85], v[98:101], v[10:25]
	v_exp_f32_e32 v4, v122
	v_exp_f32_e32 v5, v123
	v_exp_f32_e32 v6, v124
	v_exp_f32_e32 v7, v125
	v_exp_f32_e32 v74, v126
	v_add_f32_e32 v1, 0, v4
	v_exp_f32_e32 v75, v127
	v_add_f32_e32 v1, v5, v1
	v_exp_f32_e32 v76, v128
	v_add_f32_e32 v1, v6, v1
	v_exp_f32_e32 v77, v129
	v_add_f32_e32 v1, v7, v1
	v_exp_f32_e32 v78, v130
	v_add_f32_e32 v1, v74, v1
	v_exp_f32_e32 v79, v131
	v_add_f32_e32 v1, v75, v1
	v_exp_f32_e32 v80, v132
	v_add_f32_e32 v1, v76, v1
	v_exp_f32_e32 v81, v133
	v_add_f32_e32 v1, v77, v1
	v_exp_f32_e32 v82, v134
	v_add_f32_e32 v1, v78, v1
	v_exp_f32_e32 v83, v135
	v_add_f32_e32 v1, v79, v1
	v_exp_f32_e32 v84, v136
	v_add_f32_e32 v1, v80, v1
	v_exp_f32_e32 v85, v137
	v_add_f32_e32 v1, v81, v1
	v_exp_f32_e32 v86, v106
	v_add_f32_e32 v1, v82, v1
	v_exp_f32_e32 v87, v107
	v_add_f32_e32 v1, v83, v1
	v_exp_f32_e32 v88, v108
	v_add_f32_e32 v1, v84, v1
	v_exp_f32_e32 v89, v109
	v_add_f32_e32 v1, v85, v1
	v_exp_f32_e32 v90, v110
	v_add_f32_e32 v1, v86, v1
	v_exp_f32_e32 v91, v111
	v_add_f32_e32 v1, v87, v1
	v_exp_f32_e32 v92, v112
	v_add_f32_e32 v1, v88, v1
	v_exp_f32_e32 v93, v113
	v_add_f32_e32 v1, v89, v1
	v_exp_f32_e32 v94, v114
	v_add_f32_e32 v1, v90, v1
	v_exp_f32_e32 v95, v115
	v_add_f32_e32 v1, v91, v1
	v_exp_f32_e32 v96, v116
	v_add_f32_e32 v1, v92, v1
	v_exp_f32_e32 v97, v117
	v_add_f32_e32 v1, v93, v1
	v_exp_f32_e32 v98, v118
	v_add_f32_e32 v1, v94, v1
	v_exp_f32_e32 v99, v119
	v_add_f32_e32 v1, v95, v1
	v_exp_f32_e32 v100, v120
	v_add_f32_e32 v1, v96, v1
	v_exp_f32_e32 v101, v121
	v_add_f32_e32 v1, v97, v1
	v_add_f32_e32 v1, v98, v1
	v_add_f32_e32 v1, v99, v1
	v_add_f32_e32 v1, v100, v1
	v_add_f32_e32 v1, v101, v1
	v_mov_b32_e32 v3, v1
	s_waitcnt vmcnt(0)
	s_barrier
; #define ATT_GAS __attribute__((address_space(1)))
; __device__ __forceinline__ int crow(int r, int hi) { return (r & 3) + 8 * (r >> 2) + 4 * hi; }
; __device__ __forceinline__ float bf2f(bf16 v) { return __uint_as_float((unsigned)v << 16); }
; __device__ __forceinline__ bf16 f2bf(float f) { unsigned u = __float_as_uint(f); return (bf16)((u + 0x7fffu + ((u >> 16) & 1u)) >> 16); }
; template <int J> ...
;     ...
;   pv_d0(o, vb0 + (int)SHM_V, pa0, pa1, pa2, pa3);
;   if (hi == 0) li_l[r32] = l_reg; asm volatile("s_waitcnt lgkmcnt(0)" ::: "memory");
;   float rli[16];
; #pragma unroll
;   for (int r = 0; r < 16; ++r) rli[r] = __builtin_amdgcn_rcpf(li_l[crow(r, hi)]);
;   bf16* Ow = Ob + (long)(wid * QBLK) * LD; const float lam = (J == 0) ? *(const float*)(lds + SHM_ATTN + 4) : 0.f;
; #pragma unroll
;   for (int r = 0; r < 16; ++r) { const int orow = crow(r, hi);
;     if (wid * QBLK + orow < nvalid) {
; #pragma unroll
;       for (int d0 = 0; d0 < 4; ++d0) { ATT_GAS bf16* p = (ATT_GAS bf16*)(Ow + (long)orow * LD + d0 * 32 + r32); const float v = o[d0][r] * rli[r];
;         if (J == 1) *p = f2bf(v); else *p = f2bf(v - lam * bf2f(*p)); } } }
	s_nop 0
	v_permlane32_swap_b32_e32 v1, v3
	v_cvt_pk_bf16_f32 v4, v4, v5
	v_cvt_pk_bf16_f32 v5, v6, v7
	v_cvt_pk_bf16_f32 v6, v74, v75
	v_cvt_pk_bf16_f32 v7, v76, v77
	v_cvt_pk_bf16_f32 v74, v78, v79
	v_cvt_pk_bf16_f32 v75, v80, v81
	v_cvt_pk_bf16_f32 v76, v82, v83
	v_cvt_pk_bf16_f32 v77, v84, v85
	v_cvt_pk_bf16_f32 v78, v86, v87
	v_cvt_pk_bf16_f32 v79, v88, v89
	v_cvt_pk_bf16_f32 v80, v90, v91
	v_cvt_pk_bf16_f32 v81, v92, v93
	v_cvt_pk_bf16_f32 v82, v94, v95
	v_cvt_pk_bf16_f32 v83, v96, v97
	v_cvt_pk_bf16_f32 v84, v98, v99
	v_cvt_pk_bf16_f32 v85, v100, v101
	s_nop 0
	v_permlane32_swap_b32_e32 v4, v6
	v_permlane32_swap_b32_e32 v5, v7
	v_permlane32_swap_b32_e32 v74, v76
	v_permlane32_swap_b32_e32 v75, v77
	v_permlane32_swap_b32_e32 v78, v80
	v_permlane32_swap_b32_e32 v79, v81
	v_permlane32_swap_b32_e32 v82, v84
	v_permlane32_swap_b32_e32 v83, v85
	s_cmp_lg_u32 0, -1
	s_cselect_b32 s1, 0, 0
	s_addk_i32 s1, 0x4000
	s_waitcnt lgkmcnt(0)
	v_add_u32_e32 v102, s1, v215
	ds_read_b64_tr_b16 v[86:87], v102 offset:0
	ds_read_b64_tr_b16 v[88:89], v102 offset:0x800
	ds_read_b64_tr_b16 v[90:91], v102 offset:0x1000
	ds_read_b64_tr_b16 v[92:93], v102 offset:0x1800
	ds_read_b64_tr_b16 v[94:95], v102 offset:0x2000
	ds_read_b64_tr_b16 v[96:97], v102 offset:0x2800
	ds_read_b64_tr_b16 v[98:99], v102 offset:0x3000
	ds_read_b64_tr_b16 v[100:101], v102 offset:0x3800
	s_waitcnt lgkmcnt(4)
	s_nop 0
	v_mfma_f32_32x32x16_bf16 v[58:73], v[4:7], v[86:89], v[58:73]
	ds_read_b64_tr_b16 v[86:87], v102 offset:0x200
	ds_read_b64_tr_b16 v[88:89], v102 offset:0xa00
	v_mfma_f32_32x32x16_bf16 v[58:73], v[74:77], v[90:93], v[58:73]
	ds_read_b64_tr_b16 v[90:91], v102 offset:0x1200
	ds_read_b64_tr_b16 v[92:93], v102 offset:0x1a00
	s_waitcnt lgkmcnt(4)
	v_mfma_f32_32x32x16_bf16 v[58:73], v[78:81], v[94:97], v[58:73]
	ds_read_b64_tr_b16 v[94:95], v102 offset:0x2200
	ds_read_b64_tr_b16 v[96:97], v102 offset:0x2a00
	v_mfma_f32_32x32x16_bf16 v[58:73], v[82:85], v[98:101], v[58:73]
	ds_read_b64_tr_b16 v[98:99], v102 offset:0x3200
	ds_read_b64_tr_b16 v[100:101], v102 offset:0x3a00
	s_waitcnt lgkmcnt(4)
	v_mfma_f32_32x32x16_bf16 v[42:57], v[4:7], v[86:89], v[42:57]
	ds_read_b64_tr_b16 v[86:87], v102 offset:0x400
	ds_read_b64_tr_b16 v[88:89], v102 offset:0xc00
	v_mfma_f32_32x32x16_bf16 v[42:57], v[74:77], v[90:93], v[42:57]
	ds_read_b64_tr_b16 v[90:91], v102 offset:0x1400
	ds_read_b64_tr_b16 v[92:93], v102 offset:0x1c00
	s_waitcnt lgkmcnt(4)
	v_mfma_f32_32x32x16_bf16 v[42:57], v[78:81], v[94:97], v[42:57]
	ds_read_b64_tr_b16 v[94:95], v102 offset:0x2400
	ds_read_b64_tr_b16 v[96:97], v102 offset:0x2c00
	v_mfma_f32_32x32x16_bf16 v[42:57], v[82:85], v[98:101], v[42:57]
	ds_read_b64_tr_b16 v[98:99], v102 offset:0x3400
	ds_read_b64_tr_b16 v[100:101], v102 offset:0x3c00
	s_waitcnt lgkmcnt(4)
	v_mfma_f32_32x32x16_bf16 v[26:41], v[4:7], v[86:89], v[26:41]
	ds_read_b64_tr_b16 v[86:87], v102 offset:0x600
	ds_read_b64_tr_b16 v[88:89], v102 offset:0xe00
	v_mfma_f32_32x32x16_bf16 v[26:41], v[74:77], v[90:93], v[26:41]
	ds_read_b64_tr_b16 v[90:91], v102 offset:0x1600
	ds_read_b64_tr_b16 v[92:93], v102 offset:0x1e00
	s_waitcnt lgkmcnt(4)
	v_mfma_f32_32x32x16_bf16 v[26:41], v[78:81], v[94:97], v[26:41]
	ds_read_b64_tr_b16 v[94:95], v102 offset:0x2600
	ds_read_b64_tr_b16 v[96:97], v102 offset:0x2e00
	v_mfma_f32_32x32x16_bf16 v[26:41], v[82:85], v[98:101], v[26:41]
	ds_read_b64_tr_b16 v[98:99], v102 offset:0x3600
	ds_read_b64_tr_b16 v[100:101], v102 offset:0x3e00
	s_waitcnt lgkmcnt(4)
	v_mfma_f32_32x32x16_bf16 v[10:25], v[4:7], v[86:89], v[10:25]
	s_waitcnt lgkmcnt(0)
	v_mfma_f32_32x32x16_bf16 v[10:25], v[74:77], v[90:93], v[10:25]
	v_mfma_f32_32x32x16_bf16 v[10:25], v[78:81], v[94:97], v[10:25]
	v_cmp_gt_u32_e32 vcc, 32, v9
	v_mfma_f32_32x32x16_bf16 v[10:25], v[82:85], v[98:101], v[10:25]
	s_and_saveexec_b64 s[4:5], vcc
	v_pk_add_f32 v[0:1], v[0:1], v[2:3]
	v_lshl_add_u32 v4, v218, 2, s0
	v_add_f32_e32 v0, v226, v0
	v_add_f32_e32 v0, v0, v1
	ds_write_b32 v4, v0
	s_or_b64 exec, exec, s[4:5]
	s_waitcnt lgkmcnt(0)
	v_lshl_add_u32 v82, v216, 2, s0
	ds_read2_b32 v[80:81], v82 offset0:1 offset1:2
	ds_read_b32 v9, v82 offset:12
	ds_read_b128 v[74:77], v82 offset:32
	ds_read_b128 v[4:7], v82 offset:64
	ds_read_b128 v[0:3], v82 offset:96
	s_ashr_i32 s7, s6, 31
	s_lshl_b64 s[0:1], s[6:7], 12
	v_readlane_b32 s2, v244, 7
	s_add_u32 s0, s2, s0
	v_readlane_b32 s2, v244, 10
	s_addc_u32 s1, s2, s1
	v_lshlrev_b32_e32 v170, 1, v218
	v_or_b32_e32 v83, s6, v216
	v_lshl_add_u64 v[78:79], s[0:1], 0, v[170:171]
	v_cmp_gt_i32_e32 vcc, s8, v83
	s_and_saveexec_b64 s[4:5], vcc
	s_cbranch_execz .LBB0_772
	ds_read_b32 v82, v82
	v_lshlrev_b32_e32 v170, 14, v217
	s_waitcnt lgkmcnt(0)
	v_rcp_f32_e32 v84, v82
	v_lshl_add_u64 v[82:83], v[78:79], 0, v[170:171]
	v_mul_f32_e32 v58, v58, v84
	v_bfe_u32 v85, v58, 16, 1
	v_add3_u32 v58, v58, v85, s26
	v_mul_f32_e32 v42, v42, v84
	global_store_short_d16_hi v[82:83], v58, off
	v_bfe_u32 v58, v42, 16, 1
	v_add3_u32 v42, v42, v58, s26
	v_mul_f32_e32 v26, v26, v84
	global_store_short_d16_hi v[82:83], v42, off offset:64
	v_bfe_u32 v42, v26, 16, 1
	v_add3_u32 v26, v26, v42, s26
	v_mul_f32_e32 v10, v10, v84
	global_store_short_d16_hi v[82:83], v26, off offset:128
	v_bfe_u32 v26, v10, 16, 1
	v_add3_u32 v10, v10, v26, s26
	global_store_short_d16_hi v[82:83], v10, off offset:192

; __global__ void __launch_bounds__(512, 2) mega_fwd(Args a_in) {
	.amdhsa_kernel _Z8mega_fwd4Args
		.amdhsa_group_segment_fixed_size 0
		.amdhsa_private_segment_fixed_size 0
		.amdhsa_kernarg_size 416
		.amdhsa_user_sgpr_count 2
		.amdhsa_user_sgpr_dispatch_ptr 0
		.amdhsa_user_sgpr_queue_ptr 0
		.amdhsa_user_sgpr_kernarg_segment_ptr 1
		.amdhsa_user_sgpr_dispatch_id 0
		.amdhsa_user_sgpr_kernarg_preload_length 0
		.amdhsa_user_sgpr_kernarg_preload_offset 0
		.amdhsa_user_sgpr_private_segment_size 0
		.amdhsa_uses_dynamic_stack 0
		.amdhsa_enable_private_segment 0
		.amdhsa_system_sgpr_workgroup_id_x 1
		.amdhsa_system_sgpr_workgroup_id_y 0
		.amdhsa_system_sgpr_workgroup_id_z 0
		.amdhsa_system_sgpr_workgroup_info 0
		.amdhsa_system_vgpr_workitem_id 2
		.amdhsa_next_free_vgpr 256
		.amdhsa_next_free_sgpr 98
		.amdhsa_accum_offset 256
		.amdhsa_reserve_vcc 1
		.amdhsa_float_round_mode_32 0
		.amdhsa_float_round_mode_16_64 0
		.amdhsa_float_denorm_mode_32 3
		.amdhsa_float_denorm_mode_16_64 3
		.amdhsa_dx10_clamp 1
		.amdhsa_ieee_mode 1
		.amdhsa_fp16_overflow 0
		.amdhsa_tg_split 0
		.amdhsa_exception_fp_ieee_invalid_op 0
		.amdhsa_exception_fp_denorm_src 0
		.amdhsa_exception_fp_ieee_div_zero 0
		.amdhsa_exception_fp_ieee_overflow 0
		.amdhsa_exception_fp_ieee_underflow 0
		.amdhsa_exception_fp_ieee_inexact 0
		.amdhsa_exception_int_div_zero 0
	.end_amdhsa_kernel

; __global__ void __launch_bounds__(512, 2) mega_fwd(Args a_in) {
amdhsa.kernels:
  - .agpr_count:     0
    .args:
      - .offset:         0
        .size:           160
        .value_kind:     by_value
      - .offset:         160
        .size:           4
        .value_kind:     hidden_block_count_x
      - .offset:         164
        .size:           4
        .value_kind:     hidden_block_count_y
      - .offset:         168
        .size:           4
        .value_kind:     hidden_block_count_z
      - .offset:         172
        .size:           2
        .value_kind:     hidden_group_size_x
      - .offset:         174
        .size:           2
        .value_kind:     hidden_group_size_y
      - .offset:         176
        .size:           2
        .value_kind:     hidden_group_size_z
      - .offset:         178
        .size:           2
        .value_kind:     hidden_remainder_x
      - .offset:         180
        .size:           2
        .value_kind:     hidden_remainder_y
      - .offset:         182
        .size:           2
        .value_kind:     hidden_remainder_z
      - .offset:         200
        .size:           8
        .value_kind:     hidden_global_offset_x
      - .offset:         208
        .size:           8
        .value_kind:     hidden_global_offset_y
      - .offset:         216
        .size:           8
        .value_kind:     hidden_global_offset_z
      - .offset:         224
        .size:           2
        .value_kind:     hidden_grid_dims
      - .offset:         248
        .size:           8
        .value_kind:     hidden_multigrid_sync_arg
      - .offset:         280
        .size:           4
        .value_kind:     hidden_dynamic_lds_size
    .group_segment_fixed_size: 0
    .kernarg_segment_align: 8
    .kernarg_segment_size: 416
    .language:       OpenCL C
    .language_version:
      - 2
      - 0
    .max_flat_workgroup_size: 512
    .name:           _Z8mega_fwd4Args
    .private_segment_fixed_size: 0
    .sgpr_count:     104
    .sgpr_spill_count: 41
    .symbol:         _Z8mega_fwd4Args.kd
    .uniform_work_group_size: 1
    .uses_dynamic_stack: false
    .vgpr_count:     256
    .vgpr_spill_count: 0
    .wavefront_size: 64
